# sample-tile up-proj epilogue: single pass, packed history loads, history term per source lane; packed f32 math
# speedup vs baseline: 1.0711x; 1.0187x over previous
; #define PG8_LAS __attribute__((address_space(3)))
;     __device__ __forceinline__ void operator()(const f32x4 (&acc)[2][2][4][2], const Unit& u, int wr, int wc, int fr, int fq) const {
;     ...
;                 if (!smp && fr >= 14 && (wr == 1 || ai == 1)) { const int sai = wr == 1 ? ai : 0, swr = wr == 1 ? 0 : 1;
;                     pa = *(const PG8_LAS f32x4*)(xch + ((((sai * 2 + swr) * 4 + wc) * 4 + fq) * 2 + (fr - 14)) * 8 + 4 * n); }
; #pragma unroll
;                 for (int m = 0; m < 4; ++m) {
;                     const int r = row0 + ai * HALF + m * 16; const float rs = rstd[ai][m];
;                     const f32x4 a = acc[ai][0][m][n] * rs, b = acc[ai][1][m][n] * rs; f32x4 p1, p2;
;                     if (!smp) {
; #pragma unroll
;                         for (int e2 = 0; e2 < 4; ++e2) { const float s1 = fr == 15 ? pa[e2] : a[e2], s2 = fr >= 14 ? pa[e2] : a[e2]; p1[e2] = ror1(s1); p2[e2] = ror2(s2); }
;                         if (ai == 0 && wr == 0 && m == 0 && fr < 2) { *(f32x4*)(EA + ((size_t)u.pm * 4 + fr) * FF + j0 + 4 * n) = a; *(f32x4*)(EB + ((size_t)u.pm * 2 + fr) * FF + j0 + 4 * n) = b; }
;                         if (ai == 1 && wr == 1 && m == 3 && fr >= 14) { *(f32x4*)(EA + ((size_t)u.pm * 4 + 2 + (fr - 14)) * FF + j0 + 4 * n) = a;
;                             if ((u.pm & 7) == 7) *(f32x4*)(o_conv_p + ((size_t)(u.pm >> 3) * 2 + (fr - 14)) * FF + j0 + 4 * n) = a; }
;                     } else {
;                         const int t = fr & 7, bb = (r - 16384) >> 3;
; #pragma unroll
;                         for (int e2 = 0; e2 < 4; ++e2) { p1[e2] = ror1(a[e2]); p2[e2] = ror2(a[e2]); }
;                         if (t < 2) { const f32x4 h1 = *(const f32x4*)(state_conv + ((size_t)bb * 2 + 1) * FF + j0 + 4 * n);
;                             if (t == 0) { p1 = h1; p2 = *(const f32x4*)(state_conv + ((size_t)bb * 2) * FF + j0 + 4 * n); } else p2 = h1; }
;                         if (t >= 6) *(f32x4*)(o_conv_s + ((size_t)bb * 2 + (t - 6)) * FF + j0 + 4 * n) = a;
;                     }
;                     f32x4 hv;
; #pragma unroll
;                     for (int e2 = 0; e2 < 1; ++e2) {
;                         const f32x4 c4 = cb + w0 * p2 + w1 * p1 + w2 * a;
;                         const f32x4 z = c4 * ((c4 * c4) * (-0.10294324f) + (-2.3022082f));
.Lepi5_pa_done:
	s_mov_b64 exec, -1
	s_and_b32 s73, s11, 1
	s_lshl_b32 s73, s73, 11
	s_add_i32 s73, s73, 0x24000
	s_lshl_b32 s74, s72, 7
	s_add_i32 s73, s73, s74
	v_lshl_add_u32 v87, v201, 5, s73
	ds_read_b128 v[226:229], v87 offset:0
	ds_read_b128 v[230:233], v87 offset:16
	ds_read_b128 v[234:237], v87 offset:512
	ds_read_b128 v[238:241], v87 offset:528
	ds_read_b128 v[242:245], v87 offset:1024
	ds_read_b128 v[246:249], v87 offset:1040
	ds_read_b128 v[250:253], v87 offset:1536
	ds_read_b128 v[204:207], v87 offset:1552
	s_waitcnt lgkmcnt(0)
	v_cndmask_b32_e64 v104, 0, v242, s[94:95]
	v_cndmask_b32_e64 v112, 0, v234, s[92:93]
	v_cndmask_b32_e64 v105, 0, v243, s[94:95]
	v_cndmask_b32_e64 v113, 0, v235, s[92:93]
	v_cndmask_b32_e64 v106, 0, v244, s[94:95]
	v_cndmask_b32_e64 v114, 0, v236, s[92:93]
	v_cndmask_b32_e64 v107, 0, v245, s[94:95]
	v_cndmask_b32_e64 v115, 0, v237, s[92:93]
	v_cndmask_b32_e64 v108, 0, v246, s[94:95]
	v_cndmask_b32_e64 v116, 0, v238, s[92:93]
	v_cndmask_b32_e64 v109, 0, v247, s[94:95]
	v_cndmask_b32_e64 v117, 0, v239, s[92:93]
	v_cndmask_b32_e64 v110, 0, v248, s[94:95]
	v_cndmask_b32_e64 v118, 0, v240, s[92:93]
	v_cndmask_b32_e64 v111, 0, v249, s[94:95]
	v_cndmask_b32_e64 v119, 0, v241, s[92:93]
	v_mov_b32_e32 v154, 0xc0135761
	v_mov_b32_e32 v155, 0xc0135761
	v_mov_b32_e32 v152, 1.0
	v_mov_b32_e32 v153, 1.0
	s_mov_b32 s42, 0xbdd2d3e8
	s_mov_b32 s43, 0xbdd2d3e8
	s_mul_i32 s73, s28, 0x160000
	s_add_u32 s80, s86, 0x9e00000
	s_addc_u32 s81, s87, 0
	s_add_u32 s80, s80, s73
	s_addc_u32 s81, s81, 0
	s_waitcnt lgkmcnt(0)
	s_cmp_lg_u32 s71, 0
	s_cbranch_scc1 .Lepi5_noedge0
	s_movk_i32 s75, 0x2c00
	v_mad_u32_u24 v99, v200, s75, v213
	s_mul_i32 s73, s28, 0xb000
	s_add_u32 s88, s86, 0x4000000
	s_addc_u32 s89, s87, 0
	s_add_u32 s88, s88, s73
	s_addc_u32 s89, s89, 0
	s_mul_i32 s73, s28, 0x5800
	s_add_u32 s34, s86, 0x4400000
	s_addc_u32 s35, s87, 0
	s_add_u32 s34, s34, s73
	s_addc_u32 s35, s35, 0
	s_mov_b64 exec, s[92:93]
	global_store_dwordx4 v99, v[148:151], s[88:89]
	global_store_dwordx4 v99, v[62:65], s[88:89] offset:16
	global_store_dwordx4 v99, v[144:147], s[34:35]
	global_store_dwordx4 v99, v[58:61], s[34:35] offset:16
	s_mov_b64 exec, -1
.Lepi5_noedge0:
	v_pk_fma_f32 v[208:209], v[148:149], v[250:251], v[226:227]
	v_pk_fma_f32 v[210:211], v[150:151], v[252:253], v[228:229]
	v_fmac_f32_dpp v208, v148, v242 row_shr:1 row_mask:0xf bank_mask:0xf
	v_fmac_f32_dpp v209, v149, v243 row_shr:1 row_mask:0xf bank_mask:0xf
	v_fmac_f32_dpp v210, v150, v244 row_shr:1 row_mask:0xf bank_mask:0xf
	v_fmac_f32_dpp v211, v151, v245 row_shr:1 row_mask:0xf bank_mask:0xf
	v_fmac_f32_dpp v208, v148, v234 row_shr:2 row_mask:0xf bank_mask:0xf
	v_fmac_f32_dpp v209, v149, v235 row_shr:2 row_mask:0xf bank_mask:0xf
	v_fmac_f32_dpp v210, v150, v236 row_shr:2 row_mask:0xf bank_mask:0xf
	v_fmac_f32_dpp v211, v151, v237 row_shr:2 row_mask:0xf bank_mask:0xf
	v_fmac_f32_dpp v208, v188, v104 row_ror:1 row_mask:0xf bank_mask:0xf
	v_fmac_f32_dpp v209, v189, v105 row_ror:1 row_mask:0xf bank_mask:0xf
	v_fmac_f32_dpp v210, v190, v106 row_ror:1 row_mask:0xf bank_mask:0xf
	v_fmac_f32_dpp v211, v191, v107 row_ror:1 row_mask:0xf bank_mask:0xf
	v_fmac_f32_dpp v208, v188, v112 row_ror:2 row_mask:0xf bank_mask:0xf
	v_fmac_f32_dpp v209, v189, v113 row_ror:2 row_mask:0xf bank_mask:0xf
	v_fmac_f32_dpp v210, v190, v114 row_ror:2 row_mask:0xf bank_mask:0xf
	v_fmac_f32_dpp v211, v191, v115 row_ror:2 row_mask:0xf bank_mask:0xf
	v_pk_mul_f32 v[86:87], v[208:209], v[208:209]
	v_pk_mul_f32 v[92:93], v[210:211], v[210:211]
	v_pk_fma_f32 v[86:87], v[86:87], s[42:43], v[154:155] op_sel_hi:[1,0,1]
	v_pk_fma_f32 v[92:93], v[92:93], s[42:43], v[154:155] op_sel_hi:[1,0,1]
	v_pk_mul_f32 v[86:87], v[208:209], v[86:87]
	v_pk_mul_f32 v[92:93], v[210:211], v[92:93]
	v_exp_f32_e32 v86, v86
	v_exp_f32_e32 v87, v87
	v_exp_f32_e32 v92, v92
	v_exp_f32_e32 v93, v93
	v_pk_mul_f32 v[208:209], v[208:209], v[144:145]
	v_pk_mul_f32 v[210:211], v[210:211], v[146:147]
	v_pk_add_f32 v[86:87], v[86:87], v[152:153]
	v_pk_add_f32 v[92:93], v[92:93], v[152:153]
	v_rcp_f32_e32 v86, v86
	v_rcp_f32_e32 v87, v87
	v_rcp_f32_e32 v92, v92
	v_rcp_f32_e32 v93, v93
	s_nop 0
	v_pk_mul_f32 v[208:209], v[208:209], v[86:87]
	v_pk_mul_f32 v[210:211], v[210:211], v[92:93]
	v_cvt_pk_bf16_f32 v144, v208, v209
	v_cvt_pk_bf16_f32 v145, v210, v211
	v_pk_fma_f32 v[208:209], v[62:63], v[204:205], v[230:231]
	v_pk_fma_f32 v[210:211], v[64:65], v[206:207], v[232:233]
	v_fmac_f32_dpp v208, v62, v246 row_shr:1 row_mask:0xf bank_mask:0xf
	v_fmac_f32_dpp v209, v63, v247 row_shr:1 row_mask:0xf bank_mask:0xf
	v_fmac_f32_dpp v210, v64, v248 row_shr:1 row_mask:0xf bank_mask:0xf
	v_fmac_f32_dpp v211, v65, v249 row_shr:1 row_mask:0xf bank_mask:0xf
	v_fmac_f32_dpp v208, v62, v238 row_shr:2 row_mask:0xf bank_mask:0xf
	v_fmac_f32_dpp v209, v63, v239 row_shr:2 row_mask:0xf bank_mask:0xf
	v_fmac_f32_dpp v210, v64, v240 row_shr:2 row_mask:0xf bank_mask:0xf
	v_fmac_f32_dpp v211, v65, v241 row_shr:2 row_mask:0xf bank_mask:0xf
	v_fmac_f32_dpp v208, v192, v108 row_ror:1 row_mask:0xf bank_mask:0xf
	v_fmac_f32_dpp v209, v193, v109 row_ror:1 row_mask:0xf bank_mask:0xf
	v_fmac_f32_dpp v210, v194, v110 row_ror:1 row_mask:0xf bank_mask:0xf
	v_fmac_f32_dpp v211, v195, v111 row_ror:1 row_mask:0xf bank_mask:0xf
	v_fmac_f32_dpp v208, v192, v116 row_ror:2 row_mask:0xf bank_mask:0xf
	v_fmac_f32_dpp v209, v193, v117 row_ror:2 row_mask:0xf bank_mask:0xf
	v_fmac_f32_dpp v210, v194, v118 row_ror:2 row_mask:0xf bank_mask:0xf
	v_fmac_f32_dpp v211, v195, v119 row_ror:2 row_mask:0xf bank_mask:0xf
	v_pk_mul_f32 v[86:87], v[208:209], v[208:209]
	v_pk_mul_f32 v[92:93], v[210:211], v[210:211]
;     __device__ __forceinline__ void operator()(const f32x4 (&acc)[2][2][4][2], const Unit& u, int wr, int wc, int fr, int fq) const {
;     ...
;                 for (int m = 0; m < 4; ++m) {
;                     const int r = row0 + ai * HALF + m * 16; const float rs = rstd[ai][m];
;                     const f32x4 a = acc[ai][0][m][n] * rs, b = acc[ai][1][m][n] * rs; f32x4 p1, p2;
;                     if (!smp) {
; #pragma unroll
;                         for (int e2 = 0; e2 < 4; ++e2) { const float s1 = fr == 15 ? pa[e2] : a[e2], s2 = fr >= 14 ? pa[e2] : a[e2]; p1[e2] = ror1(s1); p2[e2] = ror2(s2); }
;                         if (ai == 0 && wr == 0 && m == 0 && fr < 2) { *(f32x4*)(EA + ((size_t)u.pm * 4 + fr) * FF + j0 + 4 * n) = a; *(f32x4*)(EB + ((size_t)u.pm * 2 + fr) * FF + j0 + 4 * n) = b; }
;                         if (ai == 1 && wr == 1 && m == 3 && fr >= 14) { *(f32x4*)(EA + ((size_t)u.pm * 4 + 2 + (fr - 14)) * FF + j0 + 4 * n) = a;
;                             if ((u.pm & 7) == 7) *(f32x4*)(o_conv_p + ((size_t)(u.pm >> 3) * 2 + (fr - 14)) * FF + j0 + 4 * n) = a; }
;                     } else {
;                         const int t = fr & 7, bb = (r - 16384) >> 3;
; #pragma unroll
;                         for (int e2 = 0; e2 < 4; ++e2) { p1[e2] = ror1(a[e2]); p2[e2] = ror2(a[e2]); }
;                         if (t < 2) { const f32x4 h1 = *(const f32x4*)(state_conv + ((size_t)bb * 2 + 1) * FF + j0 + 4 * n);
;                             if (t == 0) { p1 = h1; p2 = *(const f32x4*)(state_conv + ((size_t)bb * 2) * FF + j0 + 4 * n); } else p2 = h1; }
;                         if (t >= 6) *(f32x4*)(o_conv_s + ((size_t)bb * 2 + (t - 6)) * FF + j0 + 4 * n) = a;
;                     }
;                     f32x4 hv;
; #pragma unroll
;                     for (int e2 = 0; e2 < 1; ++e2) {
;                         const f32x4 c4 = cb + w0 * p2 + w1 * p1 + w2 * a;
;                         const f32x4 z = c4 * ((c4 * c4) * (-0.10294324f) + (-2.3022082f));
;                         f32x4 den; den[0] = 1.f + __builtin_amdgcn_exp2f(z[0]); den[1] = 1.f + __builtin_amdgcn_exp2f(z[1]); den[2] = 1.f + __builtin_amdgcn_exp2f(z[2]); den[3] = 1.f + __builtin_amdgcn_exp2f(z[3]);
;                         f32x4 rc; rc[0] = frcp(den[0]); rc[1] = frcp(den[1]); rc[2] = frcp(den[2]); rc[3] = frcp(den[3]);
;                         hv = (c4 * rc) * b; }
	v_pk_fma_f32 v[86:87], v[86:87], s[42:43], v[154:155] op_sel_hi:[1,0,1]
	v_pk_fma_f32 v[92:93], v[92:93], s[42:43], v[154:155] op_sel_hi:[1,0,1]
	v_pk_mul_f32 v[86:87], v[208:209], v[86:87]
	v_pk_mul_f32 v[92:93], v[210:211], v[92:93]
	v_exp_f32_e32 v86, v86
	v_exp_f32_e32 v87, v87
	v_exp_f32_e32 v92, v92
	v_exp_f32_e32 v93, v93
	v_pk_mul_f32 v[208:209], v[208:209], v[58:59]
	v_pk_mul_f32 v[210:211], v[210:211], v[60:61]
	v_pk_add_f32 v[86:87], v[86:87], v[152:153]
	v_pk_add_f32 v[92:93], v[92:93], v[152:153]
	v_rcp_f32_e32 v86, v86
	v_rcp_f32_e32 v87, v87
	v_rcp_f32_e32 v92, v92
	v_rcp_f32_e32 v93, v93
	s_nop 0
	v_pk_mul_f32 v[208:209], v[208:209], v[86:87]
	v_pk_mul_f32 v[210:211], v[210:211], v[92:93]
	v_cvt_pk_bf16_f32 v146, v208, v209
	v_cvt_pk_bf16_f32 v147, v210, v211
	global_store_dwordx4 v212, v[144:147], s[80:81]
	s_add_u32 s80, s80, 0x16000
	s_addc_u32 s81, s81, 0
	v_pk_fma_f32 v[208:209], v[140:141], v[250:251], v[226:227]
	v_pk_fma_f32 v[210:211], v[142:143], v[252:253], v[228:229]
	v_fmac_f32_dpp v208, v140, v242 row_shr:1 row_mask:0xf bank_mask:0xf
	v_fmac_f32_dpp v209, v141, v243 row_shr:1 row_mask:0xf bank_mask:0xf
	v_fmac_f32_dpp v210, v142, v244 row_shr:1 row_mask:0xf bank_mask:0xf
	v_fmac_f32_dpp v211, v143, v245 row_shr:1 row_mask:0xf bank_mask:0xf
	v_fmac_f32_dpp v208, v140, v234 row_shr:2 row_mask:0xf bank_mask:0xf
	v_fmac_f32_dpp v209, v141, v235 row_shr:2 row_mask:0xf bank_mask:0xf
	v_fmac_f32_dpp v210, v142, v236 row_shr:2 row_mask:0xf bank_mask:0xf
	v_fmac_f32_dpp v211, v143, v237 row_shr:2 row_mask:0xf bank_mask:0xf
	v_fmac_f32_dpp v208, v148, v104 row_ror:1 row_mask:0xf bank_mask:0xf
	v_fmac_f32_dpp v209, v149, v105 row_ror:1 row_mask:0xf bank_mask:0xf
	v_fmac_f32_dpp v210, v150, v106 row_ror:1 row_mask:0xf bank_mask:0xf
	v_fmac_f32_dpp v211, v151, v107 row_ror:1 row_mask:0xf bank_mask:0xf
	v_fmac_f32_dpp v208, v148, v112 row_ror:2 row_mask:0xf bank_mask:0xf
	v_fmac_f32_dpp v209, v149, v113 row_ror:2 row_mask:0xf bank_mask:0xf
	v_fmac_f32_dpp v210, v150, v114 row_ror:2 row_mask:0xf bank_mask:0xf
	v_fmac_f32_dpp v211, v151, v115 row_ror:2 row_mask:0xf bank_mask:0xf
	v_pk_mul_f32 v[86:87], v[208:209], v[208:209]
	v_pk_mul_f32 v[92:93], v[210:211], v[210:211]
	v_pk_fma_f32 v[86:87], v[86:87], s[42:43], v[154:155] op_sel_hi:[1,0,1]
	v_pk_fma_f32 v[92:93], v[92:93], s[42:43], v[154:155] op_sel_hi:[1,0,1]
	v_pk_mul_f32 v[86:87], v[208:209], v[86:87]
	v_pk_mul_f32 v[92:93], v[210:211], v[92:93]
	v_exp_f32_e32 v86, v86
	v_exp_f32_e32 v87, v87
	v_exp_f32_e32 v92, v92
	v_exp_f32_e32 v93, v93
	v_pk_mul_f32 v[208:209], v[208:209], v[136:137]
	v_pk_mul_f32 v[210:211], v[210:211], v[138:139]
	v_pk_add_f32 v[86:87], v[86:87], v[152:153]
	v_pk_add_f32 v[92:93], v[92:93], v[152:153]
	v_rcp_f32_e32 v86, v86
	v_rcp_f32_e32 v87, v87
	v_rcp_f32_e32 v92, v92
	v_rcp_f32_e32 v93, v93
	s_nop 0
	v_pk_mul_f32 v[208:209], v[208:209], v[86:87]
	v_pk_mul_f32 v[210:211], v[210:211], v[92:93]
	v_cvt_pk_bf16_f32 v136, v208, v209
	v_cvt_pk_bf16_f32 v137, v210, v211
	v_pk_fma_f32 v[208:209], v[54:55], v[204:205], v[230:231]
	v_pk_fma_f32 v[210:211], v[56:57], v[206:207], v[232:233]
	v_fmac_f32_dpp v208, v54, v246 row_shr:1 row_mask:0xf bank_mask:0xf
	v_fmac_f32_dpp v209, v55, v247 row_shr:1 row_mask:0xf bank_mask:0xf
	v_fmac_f32_dpp v210, v56, v248 row_shr:1 row_mask:0xf bank_mask:0xf
	v_fmac_f32_dpp v211, v57, v249 row_shr:1 row_mask:0xf bank_mask:0xf
	v_fmac_f32_dpp v208, v54, v238 row_shr:2 row_mask:0xf bank_mask:0xf
	v_fmac_f32_dpp v209, v55, v239 row_shr:2 row_mask:0xf bank_mask:0xf
	v_fmac_f32_dpp v210, v56, v240 row_shr:2 row_mask:0xf bank_mask:0xf
	v_fmac_f32_dpp v211, v57, v241 row_shr:2 row_mask:0xf bank_mask:0xf
	v_fmac_f32_dpp v208, v62, v108 row_ror:1 row_mask:0xf bank_mask:0xf
	v_fmac_f32_dpp v209, v63, v109 row_ror:1 row_mask:0xf bank_mask:0xf
	v_fmac_f32_dpp v210, v64, v110 row_ror:1 row_mask:0xf bank_mask:0xf
	v_fmac_f32_dpp v211, v65, v111 row_ror:1 row_mask:0xf bank_mask:0xf
	v_fmac_f32_dpp v208, v62, v116 row_ror:2 row_mask:0xf bank_mask:0xf
	v_fmac_f32_dpp v209, v63, v117 row_ror:2 row_mask:0xf bank_mask:0xf
	v_fmac_f32_dpp v210, v64, v118 row_ror:2 row_mask:0xf bank_mask:0xf
	v_fmac_f32_dpp v211, v65, v119 row_ror:2 row_mask:0xf bank_mask:0xf
	v_pk_mul_f32 v[86:87], v[208:209], v[208:209]
	v_pk_mul_f32 v[92:93], v[210:211], v[210:211]
	v_pk_fma_f32 v[86:87], v[86:87], s[42:43], v[154:155] op_sel_hi:[1,0,1]
	v_pk_fma_f32 v[92:93], v[92:93], s[42:43], v[154:155] op_sel_hi:[1,0,1]
	v_pk_mul_f32 v[86:87], v[208:209], v[86:87]
	v_pk_mul_f32 v[92:93], v[210:211], v[92:93]
	v_exp_f32_e32 v86, v86
	v_exp_f32_e32 v87, v87
	v_exp_f32_e32 v92, v92
	v_exp_f32_e32 v93, v93
	v_pk_mul_f32 v[208:209], v[208:209], v[50:51]
	v_pk_mul_f32 v[210:211], v[210:211], v[52:53]
	v_pk_add_f32 v[86:87], v[86:87], v[152:153]
	v_pk_add_f32 v[92:93], v[92:93], v[152:153]
	v_rcp_f32_e32 v86, v86
	v_rcp_f32_e32 v87, v87
	v_rcp_f32_e32 v92, v92
	v_rcp_f32_e32 v93, v93
	s_nop 0
	v_pk_mul_f32 v[208:209], v[208:209], v[86:87]
	v_pk_mul_f32 v[210:211], v[210:211], v[92:93]
	v_cvt_pk_bf16_f32 v138, v208, v209
	v_cvt_pk_bf16_f32 v139, v210, v211
	global_store_dwordx4 v212, v[136:139], s[80:81]
	s_add_u32 s80, s80, 0x16000
	s_addc_u32 s81, s81, 0
	v_pk_fma_f32 v[208:209], v[132:133], v[250:251], v[226:227]
	v_pk_fma_f32 v[210:211], v[134:135], v[252:253], v[228:229]
	v_fmac_f32_dpp v208, v132, v242 row_shr:1 row_mask:0xf bank_mask:0xf
	v_fmac_f32_dpp v209, v133, v243 row_shr:1 row_mask:0xf bank_mask:0xf
	v_fmac_f32_dpp v210, v134, v244 row_shr:1 row_mask:0xf bank_mask:0xf
	v_fmac_f32_dpp v211, v135, v245 row_shr:1 row_mask:0xf bank_mask:0xf
;     __device__ __forceinline__ void operator()(const f32x4 (&acc)[2][2][4][2], const Unit& u, int wr, int wc, int fr, int fq) const {
;     ...
;                 for (int m = 0; m < 4; ++m) {
;                     const int r = row0 + ai * HALF + m * 16; const float rs = rstd[ai][m];
;                     const f32x4 a = acc[ai][0][m][n] * rs, b = acc[ai][1][m][n] * rs; f32x4 p1, p2;
;                     if (!smp) {
; #pragma unroll
;                         for (int e2 = 0; e2 < 4; ++e2) { const float s1 = fr == 15 ? pa[e2] : a[e2], s2 = fr >= 14 ? pa[e2] : a[e2]; p1[e2] = ror1(s1); p2[e2] = ror2(s2); }
;                         if (ai == 0 && wr == 0 && m == 0 && fr < 2) { *(f32x4*)(EA + ((size_t)u.pm * 4 + fr) * FF + j0 + 4 * n) = a; *(f32x4*)(EB + ((size_t)u.pm * 2 + fr) * FF + j0 + 4 * n) = b; }
;                         if (ai == 1 && wr == 1 && m == 3 && fr >= 14) { *(f32x4*)(EA + ((size_t)u.pm * 4 + 2 + (fr - 14)) * FF + j0 + 4 * n) = a;
;                             if ((u.pm & 7) == 7) *(f32x4*)(o_conv_p + ((size_t)(u.pm >> 3) * 2 + (fr - 14)) * FF + j0 + 4 * n) = a; }
;                     } else {
;                         const int t = fr & 7, bb = (r - 16384) >> 3;
; #pragma unroll
;                         for (int e2 = 0; e2 < 4; ++e2) { p1[e2] = ror1(a[e2]); p2[e2] = ror2(a[e2]); }
;                         if (t < 2) { const f32x4 h1 = *(const f32x4*)(state_conv + ((size_t)bb * 2 + 1) * FF + j0 + 4 * n);
;                             if (t == 0) { p1 = h1; p2 = *(const f32x4*)(state_conv + ((size_t)bb * 2) * FF + j0 + 4 * n); } else p2 = h1; }
;                         if (t >= 6) *(f32x4*)(o_conv_s + ((size_t)bb * 2 + (t - 6)) * FF + j0 + 4 * n) = a;
;                     }
;                     f32x4 hv;
; #pragma unroll
;                     for (int e2 = 0; e2 < 1; ++e2) {
;                         const f32x4 c4 = cb + w0 * p2 + w1 * p1 + w2 * a;
;                         const f32x4 z = c4 * ((c4 * c4) * (-0.10294324f) + (-2.3022082f));
;                         f32x4 den; den[0] = 1.f + __builtin_amdgcn_exp2f(z[0]); den[1] = 1.f + __builtin_amdgcn_exp2f(z[1]); den[2] = 1.f + __builtin_amdgcn_exp2f(z[2]); den[3] = 1.f + __builtin_amdgcn_exp2f(z[3]);
;                         f32x4 rc; rc[0] = frcp(den[0]); rc[1] = frcp(den[1]); rc[2] = frcp(den[2]); rc[3] = frcp(den[3]);
;                         hv = (c4 * rc) * b; }
	v_fmac_f32_dpp v208, v132, v234 row_shr:2 row_mask:0xf bank_mask:0xf
	v_fmac_f32_dpp v209, v133, v235 row_shr:2 row_mask:0xf bank_mask:0xf
	v_fmac_f32_dpp v210, v134, v236 row_shr:2 row_mask:0xf bank_mask:0xf
	v_fmac_f32_dpp v211, v135, v237 row_shr:2 row_mask:0xf bank_mask:0xf
	v_fmac_f32_dpp v208, v140, v104 row_ror:1 row_mask:0xf bank_mask:0xf
	v_fmac_f32_dpp v209, v141, v105 row_ror:1 row_mask:0xf bank_mask:0xf
	v_fmac_f32_dpp v210, v142, v106 row_ror:1 row_mask:0xf bank_mask:0xf
	v_fmac_f32_dpp v211, v143, v107 row_ror:1 row_mask:0xf bank_mask:0xf
	v_fmac_f32_dpp v208, v140, v112 row_ror:2 row_mask:0xf bank_mask:0xf
	v_fmac_f32_dpp v209, v141, v113 row_ror:2 row_mask:0xf bank_mask:0xf
	v_fmac_f32_dpp v210, v142, v114 row_ror:2 row_mask:0xf bank_mask:0xf
	v_fmac_f32_dpp v211, v143, v115 row_ror:2 row_mask:0xf bank_mask:0xf
	v_pk_mul_f32 v[86:87], v[208:209], v[208:209]
	v_pk_mul_f32 v[92:93], v[210:211], v[210:211]
	v_pk_fma_f32 v[86:87], v[86:87], s[42:43], v[154:155] op_sel_hi:[1,0,1]
	v_pk_fma_f32 v[92:93], v[92:93], s[42:43], v[154:155] op_sel_hi:[1,0,1]
	v_pk_mul_f32 v[86:87], v[208:209], v[86:87]
	v_pk_mul_f32 v[92:93], v[210:211], v[92:93]
	v_exp_f32_e32 v86, v86
	v_exp_f32_e32 v87, v87
	v_exp_f32_e32 v92, v92
	v_exp_f32_e32 v93, v93
	v_pk_mul_f32 v[208:209], v[208:209], v[128:129]
	v_pk_mul_f32 v[210:211], v[210:211], v[130:131]
	v_pk_add_f32 v[86:87], v[86:87], v[152:153]
	v_pk_add_f32 v[92:93], v[92:93], v[152:153]
	v_rcp_f32_e32 v86, v86
	v_rcp_f32_e32 v87, v87
	v_rcp_f32_e32 v92, v92
	v_rcp_f32_e32 v93, v93
	s_nop 0
	v_pk_mul_f32 v[208:209], v[208:209], v[86:87]
	v_pk_mul_f32 v[210:211], v[210:211], v[92:93]
	v_cvt_pk_bf16_f32 v128, v208, v209
	v_cvt_pk_bf16_f32 v129, v210, v211
	v_pk_fma_f32 v[208:209], v[46:47], v[204:205], v[230:231]
	v_pk_fma_f32 v[210:211], v[48:49], v[206:207], v[232:233]
	v_fmac_f32_dpp v208, v46, v246 row_shr:1 row_mask:0xf bank_mask:0xf
	v_fmac_f32_dpp v209, v47, v247 row_shr:1 row_mask:0xf bank_mask:0xf
	v_fmac_f32_dpp v210, v48, v248 row_shr:1 row_mask:0xf bank_mask:0xf
	v_fmac_f32_dpp v211, v49, v249 row_shr:1 row_mask:0xf bank_mask:0xf
	v_fmac_f32_dpp v208, v46, v238 row_shr:2 row_mask:0xf bank_mask:0xf
	v_fmac_f32_dpp v209, v47, v239 row_shr:2 row_mask:0xf bank_mask:0xf
	v_fmac_f32_dpp v210, v48, v240 row_shr:2 row_mask:0xf bank_mask:0xf
	v_fmac_f32_dpp v211, v49, v241 row_shr:2 row_mask:0xf bank_mask:0xf
	v_fmac_f32_dpp v208, v54, v108 row_ror:1 row_mask:0xf bank_mask:0xf
	v_fmac_f32_dpp v209, v55, v109 row_ror:1 row_mask:0xf bank_mask:0xf
	v_fmac_f32_dpp v210, v56, v110 row_ror:1 row_mask:0xf bank_mask:0xf
	v_fmac_f32_dpp v211, v57, v111 row_ror:1 row_mask:0xf bank_mask:0xf
	v_fmac_f32_dpp v208, v54, v116 row_ror:2 row_mask:0xf bank_mask:0xf
	v_fmac_f32_dpp v209, v55, v117 row_ror:2 row_mask:0xf bank_mask:0xf
	v_fmac_f32_dpp v210, v56, v118 row_ror:2 row_mask:0xf bank_mask:0xf
	v_fmac_f32_dpp v211, v57, v119 row_ror:2 row_mask:0xf bank_mask:0xf
	v_pk_mul_f32 v[86:87], v[208:209], v[208:209]
	v_pk_mul_f32 v[92:93], v[210:211], v[210:211]
	v_pk_fma_f32 v[86:87], v[86:87], s[42:43], v[154:155] op_sel_hi:[1,0,1]
	v_pk_fma_f32 v[92:93], v[92:93], s[42:43], v[154:155] op_sel_hi:[1,0,1]
	v_pk_mul_f32 v[86:87], v[208:209], v[86:87]
	v_pk_mul_f32 v[92:93], v[210:211], v[92:93]
	v_exp_f32_e32 v86, v86
	v_exp_f32_e32 v87, v87
	v_exp_f32_e32 v92, v92
	v_exp_f32_e32 v93, v93
	v_pk_mul_f32 v[208:209], v[208:209], v[42:43]
	v_pk_mul_f32 v[210:211], v[210:211], v[44:45]
	v_pk_add_f32 v[86:87], v[86:87], v[152:153]
	v_pk_add_f32 v[92:93], v[92:93], v[152:153]
	v_rcp_f32_e32 v86, v86
	v_rcp_f32_e32 v87, v87
	v_rcp_f32_e32 v92, v92
	v_rcp_f32_e32 v93, v93
	s_nop 0
	v_pk_mul_f32 v[208:209], v[208:209], v[86:87]
	v_pk_mul_f32 v[210:211], v[210:211], v[92:93]
	v_cvt_pk_bf16_f32 v130, v208, v209
	v_cvt_pk_bf16_f32 v131, v210, v211
	global_store_dwordx4 v212, v[128:131], s[80:81]
	s_add_u32 s80, s80, 0x16000
	s_addc_u32 s81, s81, 0
	v_pk_fma_f32 v[208:209], v[124:125], v[250:251], v[226:227]
	v_pk_fma_f32 v[210:211], v[126:127], v[252:253], v[228:229]
	v_fmac_f32_dpp v208, v124, v242 row_shr:1 row_mask:0xf bank_mask:0xf
	v_fmac_f32_dpp v209, v125, v243 row_shr:1 row_mask:0xf bank_mask:0xf
	v_fmac_f32_dpp v210, v126, v244 row_shr:1 row_mask:0xf bank_mask:0xf
	v_fmac_f32_dpp v211, v127, v245 row_shr:1 row_mask:0xf bank_mask:0xf
	v_fmac_f32_dpp v208, v124, v234 row_shr:2 row_mask:0xf bank_mask:0xf
	v_fmac_f32_dpp v209, v125, v235 row_shr:2 row_mask:0xf bank_mask:0xf
	v_fmac_f32_dpp v210, v126, v236 row_shr:2 row_mask:0xf bank_mask:0xf
	v_fmac_f32_dpp v211, v127, v237 row_shr:2 row_mask:0xf bank_mask:0xf
	v_fmac_f32_dpp v208, v132, v104 row_ror:1 row_mask:0xf bank_mask:0xf
	v_fmac_f32_dpp v209, v133, v105 row_ror:1 row_mask:0xf bank_mask:0xf
	v_fmac_f32_dpp v210, v134, v106 row_ror:1 row_mask:0xf bank_mask:0xf
	v_fmac_f32_dpp v211, v135, v107 row_ror:1 row_mask:0xf bank_mask:0xf
	v_fmac_f32_dpp v208, v132, v112 row_ror:2 row_mask:0xf bank_mask:0xf
	v_fmac_f32_dpp v209, v133, v113 row_ror:2 row_mask:0xf bank_mask:0xf
	v_fmac_f32_dpp v210, v134, v114 row_ror:2 row_mask:0xf bank_mask:0xf
	v_fmac_f32_dpp v211, v135, v115 row_ror:2 row_mask:0xf bank_mask:0xf
	v_pk_mul_f32 v[86:87], v[208:209], v[208:209]
	v_pk_mul_f32 v[92:93], v[210:211], v[210:211]
	v_pk_fma_f32 v[86:87], v[86:87], s[42:43], v[154:155] op_sel_hi:[1,0,1]
	v_pk_fma_f32 v[92:93], v[92:93], s[42:43], v[154:155] op_sel_hi:[1,0,1]
	v_pk_mul_f32 v[86:87], v[208:209], v[86:87]
	v_pk_mul_f32 v[92:93], v[210:211], v[92:93]
	v_exp_f32_e32 v86, v86
	v_exp_f32_e32 v87, v87
	v_exp_f32_e32 v92, v92
	v_exp_f32_e32 v93, v93
	v_pk_mul_f32 v[208:209], v[208:209], v[94:95]
;     __device__ __forceinline__ void operator()(const f32x4 (&acc)[2][2][4][2], const Unit& u, int wr, int wc, int fr, int fq) const {
;     ...
;                 for (int m = 0; m < 4; ++m) {
;                     const int r = row0 + ai * HALF + m * 16; const float rs = rstd[ai][m];
;                     const f32x4 a = acc[ai][0][m][n] * rs, b = acc[ai][1][m][n] * rs; f32x4 p1, p2;
;                     if (!smp) {
; #pragma unroll
;                         for (int e2 = 0; e2 < 4; ++e2) { const float s1 = fr == 15 ? pa[e2] : a[e2], s2 = fr >= 14 ? pa[e2] : a[e2]; p1[e2] = ror1(s1); p2[e2] = ror2(s2); }
;                         if (ai == 0 && wr == 0 && m == 0 && fr < 2) { *(f32x4*)(EA + ((size_t)u.pm * 4 + fr) * FF + j0 + 4 * n) = a; *(f32x4*)(EB + ((size_t)u.pm * 2 + fr) * FF + j0 + 4 * n) = b; }
;                         if (ai == 1 && wr == 1 && m == 3 && fr >= 14) { *(f32x4*)(EA + ((size_t)u.pm * 4 + 2 + (fr - 14)) * FF + j0 + 4 * n) = a;
;                             if ((u.pm & 7) == 7) *(f32x4*)(o_conv_p + ((size_t)(u.pm >> 3) * 2 + (fr - 14)) * FF + j0 + 4 * n) = a; }
;                     } else {
;                         const int t = fr & 7, bb = (r - 16384) >> 3;
; #pragma unroll
;                         for (int e2 = 0; e2 < 4; ++e2) { p1[e2] = ror1(a[e2]); p2[e2] = ror2(a[e2]); }
;                         if (t < 2) { const f32x4 h1 = *(const f32x4*)(state_conv + ((size_t)bb * 2 + 1) * FF + j0 + 4 * n);
;                             if (t == 0) { p1 = h1; p2 = *(const f32x4*)(state_conv + ((size_t)bb * 2) * FF + j0 + 4 * n); } else p2 = h1; }
;                         if (t >= 6) *(f32x4*)(o_conv_s + ((size_t)bb * 2 + (t - 6)) * FF + j0 + 4 * n) = a;
;                     }
;                     f32x4 hv;
; #pragma unroll
;                     for (int e2 = 0; e2 < 1; ++e2) {
;                         const f32x4 c4 = cb + w0 * p2 + w1 * p1 + w2 * a;
;                         const f32x4 z = c4 * ((c4 * c4) * (-0.10294324f) + (-2.3022082f));
;                         f32x4 den; den[0] = 1.f + __builtin_amdgcn_exp2f(z[0]); den[1] = 1.f + __builtin_amdgcn_exp2f(z[1]); den[2] = 1.f + __builtin_amdgcn_exp2f(z[2]); den[3] = 1.f + __builtin_amdgcn_exp2f(z[3]);
;                         f32x4 rc; rc[0] = frcp(den[0]); rc[1] = frcp(den[1]); rc[2] = frcp(den[2]); rc[3] = frcp(den[3]);
;                         hv = (c4 * rc) * b; }
	v_pk_mul_f32 v[210:211], v[210:211], v[96:97]
	v_pk_add_f32 v[86:87], v[86:87], v[152:153]
	v_pk_add_f32 v[92:93], v[92:93], v[152:153]
	v_rcp_f32_e32 v86, v86
	v_rcp_f32_e32 v87, v87
	v_rcp_f32_e32 v92, v92
	v_rcp_f32_e32 v93, v93
	s_nop 0
	v_pk_mul_f32 v[208:209], v[208:209], v[86:87]
	v_pk_mul_f32 v[210:211], v[210:211], v[92:93]
	v_cvt_pk_bf16_f32 v94, v208, v209
	v_cvt_pk_bf16_f32 v95, v210, v211
	v_pk_fma_f32 v[208:209], v[38:39], v[204:205], v[230:231]
	v_pk_fma_f32 v[210:211], v[40:41], v[206:207], v[232:233]
	v_fmac_f32_dpp v208, v38, v246 row_shr:1 row_mask:0xf bank_mask:0xf
	v_fmac_f32_dpp v209, v39, v247 row_shr:1 row_mask:0xf bank_mask:0xf
	v_fmac_f32_dpp v210, v40, v248 row_shr:1 row_mask:0xf bank_mask:0xf
	v_fmac_f32_dpp v211, v41, v249 row_shr:1 row_mask:0xf bank_mask:0xf
	v_fmac_f32_dpp v208, v38, v238 row_shr:2 row_mask:0xf bank_mask:0xf
	v_fmac_f32_dpp v209, v39, v239 row_shr:2 row_mask:0xf bank_mask:0xf
	v_fmac_f32_dpp v210, v40, v240 row_shr:2 row_mask:0xf bank_mask:0xf
	v_fmac_f32_dpp v211, v41, v241 row_shr:2 row_mask:0xf bank_mask:0xf
	v_fmac_f32_dpp v208, v46, v108 row_ror:1 row_mask:0xf bank_mask:0xf
	v_fmac_f32_dpp v209, v47, v109 row_ror:1 row_mask:0xf bank_mask:0xf
	v_fmac_f32_dpp v210, v48, v110 row_ror:1 row_mask:0xf bank_mask:0xf
	v_fmac_f32_dpp v211, v49, v111 row_ror:1 row_mask:0xf bank_mask:0xf
	v_fmac_f32_dpp v208, v46, v116 row_ror:2 row_mask:0xf bank_mask:0xf
	v_fmac_f32_dpp v209, v47, v117 row_ror:2 row_mask:0xf bank_mask:0xf
	v_fmac_f32_dpp v210, v48, v118 row_ror:2 row_mask:0xf bank_mask:0xf
	v_fmac_f32_dpp v211, v49, v119 row_ror:2 row_mask:0xf bank_mask:0xf
	v_pk_mul_f32 v[86:87], v[208:209], v[208:209]
	v_pk_mul_f32 v[92:93], v[210:211], v[210:211]
	v_pk_fma_f32 v[86:87], v[86:87], s[42:43], v[154:155] op_sel_hi:[1,0,1]
	v_pk_fma_f32 v[92:93], v[92:93], s[42:43], v[154:155] op_sel_hi:[1,0,1]
	v_pk_mul_f32 v[86:87], v[208:209], v[86:87]
	v_pk_mul_f32 v[92:93], v[210:211], v[92:93]
	v_exp_f32_e32 v86, v86
	v_exp_f32_e32 v87, v87
	v_exp_f32_e32 v92, v92
	v_exp_f32_e32 v93, v93
	v_pk_mul_f32 v[208:209], v[208:209], v[34:35]
	v_pk_mul_f32 v[210:211], v[210:211], v[36:37]
	v_pk_add_f32 v[86:87], v[86:87], v[152:153]
	v_pk_add_f32 v[92:93], v[92:93], v[152:153]
	v_rcp_f32_e32 v86, v86
	v_rcp_f32_e32 v87, v87
	v_rcp_f32_e32 v92, v92
	v_rcp_f32_e32 v93, v93
	s_nop 0
	v_pk_mul_f32 v[208:209], v[208:209], v[86:87]
	v_pk_mul_f32 v[210:211], v[210:211], v[92:93]
	v_cvt_pk_bf16_f32 v96, v208, v209
	v_cvt_pk_bf16_f32 v97, v210, v211
	global_store_dwordx4 v212, v[94:97], s[80:81]
	s_add_u32 s80, s80, 0x6e000
	s_addc_u32 s81, s81, 0
	v_pk_fma_f32 v[208:209], v[120:121], v[250:251], v[226:227]
	v_pk_fma_f32 v[210:211], v[122:123], v[252:253], v[228:229]
	v_fmac_f32_dpp v208, v120, v242 row_shr:1 row_mask:0xf bank_mask:0xf
	v_fmac_f32_dpp v209, v121, v243 row_shr:1 row_mask:0xf bank_mask:0xf
	v_fmac_f32_dpp v210, v122, v244 row_shr:1 row_mask:0xf bank_mask:0xf
	v_fmac_f32_dpp v211, v123, v245 row_shr:1 row_mask:0xf bank_mask:0xf
	v_fmac_f32_dpp v208, v120, v234 row_shr:2 row_mask:0xf bank_mask:0xf
	v_fmac_f32_dpp v209, v121, v235 row_shr:2 row_mask:0xf bank_mask:0xf
	v_fmac_f32_dpp v210, v122, v236 row_shr:2 row_mask:0xf bank_mask:0xf
	v_fmac_f32_dpp v211, v123, v237 row_shr:2 row_mask:0xf bank_mask:0xf
	v_fmac_f32_dpp v208, v196, v104 row_ror:1 row_mask:0xf bank_mask:0xf
	v_fmac_f32_dpp v209, v197, v105 row_ror:1 row_mask:0xf bank_mask:0xf
	v_fmac_f32_dpp v210, v198, v106 row_ror:1 row_mask:0xf bank_mask:0xf
	v_fmac_f32_dpp v211, v199, v107 row_ror:1 row_mask:0xf bank_mask:0xf
	v_fmac_f32_dpp v208, v196, v112 row_ror:2 row_mask:0xf bank_mask:0xf
	v_fmac_f32_dpp v209, v197, v113 row_ror:2 row_mask:0xf bank_mask:0xf
	v_fmac_f32_dpp v210, v198, v114 row_ror:2 row_mask:0xf bank_mask:0xf
	v_fmac_f32_dpp v211, v199, v115 row_ror:2 row_mask:0xf bank_mask:0xf
	v_pk_mul_f32 v[86:87], v[208:209], v[208:209]
	v_pk_mul_f32 v[92:93], v[210:211], v[210:211]
	v_pk_fma_f32 v[86:87], v[86:87], s[42:43], v[154:155] op_sel_hi:[1,0,1]
	v_pk_fma_f32 v[92:93], v[92:93], s[42:43], v[154:155] op_sel_hi:[1,0,1]
	v_pk_mul_f32 v[86:87], v[208:209], v[86:87]
	v_pk_mul_f32 v[92:93], v[210:211], v[92:93]
	v_exp_f32_e32 v86, v86
	v_exp_f32_e32 v87, v87
	v_exp_f32_e32 v92, v92
	v_exp_f32_e32 v93, v93
	v_pk_mul_f32 v[208:209], v[208:209], v[100:101]
	v_pk_mul_f32 v[210:211], v[210:211], v[102:103]
	v_pk_add_f32 v[86:87], v[86:87], v[152:153]
	v_pk_add_f32 v[92:93], v[92:93], v[152:153]
	v_rcp_f32_e32 v86, v86
	v_rcp_f32_e32 v87, v87
	v_rcp_f32_e32 v92, v92
	v_rcp_f32_e32 v93, v93
	s_nop 0
	v_pk_mul_f32 v[208:209], v[208:209], v[86:87]
	v_pk_mul_f32 v[210:211], v[210:211], v[92:93]
	v_cvt_pk_bf16_f32 v100, v208, v209
	v_cvt_pk_bf16_f32 v101, v210, v211
	v_pk_fma_f32 v[208:209], v[30:31], v[204:205], v[230:231]
	v_pk_fma_f32 v[210:211], v[32:33], v[206:207], v[232:233]
	v_fmac_f32_dpp v208, v30, v246 row_shr:1 row_mask:0xf bank_mask:0xf
	v_fmac_f32_dpp v209, v31, v247 row_shr:1 row_mask:0xf bank_mask:0xf
	v_fmac_f32_dpp v210, v32, v248 row_shr:1 row_mask:0xf bank_mask:0xf
	v_fmac_f32_dpp v211, v33, v249 row_shr:1 row_mask:0xf bank_mask:0xf
	v_fmac_f32_dpp v208, v30, v238 row_shr:2 row_mask:0xf bank_mask:0xf
	v_fmac_f32_dpp v209, v31, v239 row_shr:2 row_mask:0xf bank_mask:0xf
	v_fmac_f32_dpp v210, v32, v240 row_shr:2 row_mask:0xf bank_mask:0xf
	v_fmac_f32_dpp v211, v33, v241 row_shr:2 row_mask:0xf bank_mask:0xf
	v_fmac_f32_dpp v208, v160, v108 row_ror:1 row_mask:0xf bank_mask:0xf
	v_fmac_f32_dpp v209, v161, v109 row_ror:1 row_mask:0xf bank_mask:0xf
	v_fmac_f32_dpp v210, v162, v110 row_ror:1 row_mask:0xf bank_mask:0xf
;     __device__ __forceinline__ void operator()(const f32x4 (&acc)[2][2][4][2], const Unit& u, int wr, int wc, int fr, int fq) const {
;     ...
;                 for (int m = 0; m < 4; ++m) {
;                     const int r = row0 + ai * HALF + m * 16; const float rs = rstd[ai][m];
;                     const f32x4 a = acc[ai][0][m][n] * rs, b = acc[ai][1][m][n] * rs; f32x4 p1, p2;
;                     if (!smp) {
; #pragma unroll
;                         for (int e2 = 0; e2 < 4; ++e2) { const float s1 = fr == 15 ? pa[e2] : a[e2], s2 = fr >= 14 ? pa[e2] : a[e2]; p1[e2] = ror1(s1); p2[e2] = ror2(s2); }
;                         if (ai == 0 && wr == 0 && m == 0 && fr < 2) { *(f32x4*)(EA + ((size_t)u.pm * 4 + fr) * FF + j0 + 4 * n) = a; *(f32x4*)(EB + ((size_t)u.pm * 2 + fr) * FF + j0 + 4 * n) = b; }
;                         if (ai == 1 && wr == 1 && m == 3 && fr >= 14) { *(f32x4*)(EA + ((size_t)u.pm * 4 + 2 + (fr - 14)) * FF + j0 + 4 * n) = a;
;                             if ((u.pm & 7) == 7) *(f32x4*)(o_conv_p + ((size_t)(u.pm >> 3) * 2 + (fr - 14)) * FF + j0 + 4 * n) = a; }
;                     } else {
;                         const int t = fr & 7, bb = (r - 16384) >> 3;
; #pragma unroll
;                         for (int e2 = 0; e2 < 4; ++e2) { p1[e2] = ror1(a[e2]); p2[e2] = ror2(a[e2]); }
;                         if (t < 2) { const f32x4 h1 = *(const f32x4*)(state_conv + ((size_t)bb * 2 + 1) * FF + j0 + 4 * n);
;                             if (t == 0) { p1 = h1; p2 = *(const f32x4*)(state_conv + ((size_t)bb * 2) * FF + j0 + 4 * n); } else p2 = h1; }
;                         if (t >= 6) *(f32x4*)(o_conv_s + ((size_t)bb * 2 + (t - 6)) * FF + j0 + 4 * n) = a;
;                     }
;                     f32x4 hv;
; #pragma unroll
;                     for (int e2 = 0; e2 < 1; ++e2) {
;                         const f32x4 c4 = cb + w0 * p2 + w1 * p1 + w2 * a;
;                         const f32x4 z = c4 * ((c4 * c4) * (-0.10294324f) + (-2.3022082f));
;                         f32x4 den; den[0] = 1.f + __builtin_amdgcn_exp2f(z[0]); den[1] = 1.f + __builtin_amdgcn_exp2f(z[1]); den[2] = 1.f + __builtin_amdgcn_exp2f(z[2]); den[3] = 1.f + __builtin_amdgcn_exp2f(z[3]);
;                         f32x4 rc; rc[0] = frcp(den[0]); rc[1] = frcp(den[1]); rc[2] = frcp(den[2]); rc[3] = frcp(den[3]);
;                         hv = (c4 * rc) * b; }
	v_fmac_f32_dpp v211, v163, v111 row_ror:1 row_mask:0xf bank_mask:0xf
	v_fmac_f32_dpp v208, v160, v116 row_ror:2 row_mask:0xf bank_mask:0xf
	v_fmac_f32_dpp v209, v161, v117 row_ror:2 row_mask:0xf bank_mask:0xf
	v_fmac_f32_dpp v210, v162, v118 row_ror:2 row_mask:0xf bank_mask:0xf
	v_fmac_f32_dpp v211, v163, v119 row_ror:2 row_mask:0xf bank_mask:0xf
	v_pk_mul_f32 v[86:87], v[208:209], v[208:209]
	v_pk_mul_f32 v[92:93], v[210:211], v[210:211]
	v_pk_fma_f32 v[86:87], v[86:87], s[42:43], v[154:155] op_sel_hi:[1,0,1]
	v_pk_fma_f32 v[92:93], v[92:93], s[42:43], v[154:155] op_sel_hi:[1,0,1]
	v_pk_mul_f32 v[86:87], v[208:209], v[86:87]
	v_pk_mul_f32 v[92:93], v[210:211], v[92:93]
	v_exp_f32_e32 v86, v86
	v_exp_f32_e32 v87, v87
	v_exp_f32_e32 v92, v92
	v_exp_f32_e32 v93, v93
	v_pk_mul_f32 v[208:209], v[208:209], v[26:27]
	v_pk_mul_f32 v[210:211], v[210:211], v[28:29]
	v_pk_add_f32 v[86:87], v[86:87], v[152:153]
	v_pk_add_f32 v[92:93], v[92:93], v[152:153]
	v_rcp_f32_e32 v86, v86
	v_rcp_f32_e32 v87, v87
	v_rcp_f32_e32 v92, v92
	v_rcp_f32_e32 v93, v93
	s_nop 0
	v_pk_mul_f32 v[208:209], v[208:209], v[86:87]
	v_pk_mul_f32 v[210:211], v[210:211], v[92:93]
	v_cvt_pk_bf16_f32 v102, v208, v209
	v_cvt_pk_bf16_f32 v103, v210, v211
	global_store_dwordx4 v212, v[100:103], s[80:81]
	s_add_u32 s80, s80, 0x16000
	s_addc_u32 s81, s81, 0
	v_pk_fma_f32 v[208:209], v[88:89], v[250:251], v[226:227]
	v_pk_fma_f32 v[210:211], v[90:91], v[252:253], v[228:229]
	v_fmac_f32_dpp v208, v88, v242 row_shr:1 row_mask:0xf bank_mask:0xf
	v_fmac_f32_dpp v209, v89, v243 row_shr:1 row_mask:0xf bank_mask:0xf
	v_fmac_f32_dpp v210, v90, v244 row_shr:1 row_mask:0xf bank_mask:0xf
	v_fmac_f32_dpp v211, v91, v245 row_shr:1 row_mask:0xf bank_mask:0xf
	v_fmac_f32_dpp v208, v88, v234 row_shr:2 row_mask:0xf bank_mask:0xf
	v_fmac_f32_dpp v209, v89, v235 row_shr:2 row_mask:0xf bank_mask:0xf
	v_fmac_f32_dpp v210, v90, v236 row_shr:2 row_mask:0xf bank_mask:0xf
	v_fmac_f32_dpp v211, v91, v237 row_shr:2 row_mask:0xf bank_mask:0xf
	v_fmac_f32_dpp v208, v120, v104 row_ror:1 row_mask:0xf bank_mask:0xf
	v_fmac_f32_dpp v209, v121, v105 row_ror:1 row_mask:0xf bank_mask:0xf
	v_fmac_f32_dpp v210, v122, v106 row_ror:1 row_mask:0xf bank_mask:0xf
	v_fmac_f32_dpp v211, v123, v107 row_ror:1 row_mask:0xf bank_mask:0xf
	v_fmac_f32_dpp v208, v120, v112 row_ror:2 row_mask:0xf bank_mask:0xf
	v_fmac_f32_dpp v209, v121, v113 row_ror:2 row_mask:0xf bank_mask:0xf
	v_fmac_f32_dpp v210, v122, v114 row_ror:2 row_mask:0xf bank_mask:0xf
	v_fmac_f32_dpp v211, v123, v115 row_ror:2 row_mask:0xf bank_mask:0xf
	v_pk_mul_f32 v[86:87], v[208:209], v[208:209]
	v_pk_mul_f32 v[92:93], v[210:211], v[210:211]
	v_pk_fma_f32 v[86:87], v[86:87], s[42:43], v[154:155] op_sel_hi:[1,0,1]
	v_pk_fma_f32 v[92:93], v[92:93], s[42:43], v[154:155] op_sel_hi:[1,0,1]
	v_pk_mul_f32 v[86:87], v[208:209], v[86:87]
	v_pk_mul_f32 v[92:93], v[210:211], v[92:93]
	v_exp_f32_e32 v86, v86
	v_exp_f32_e32 v87, v87
	v_exp_f32_e32 v92, v92
	v_exp_f32_e32 v93, v93
	v_pk_mul_f32 v[208:209], v[208:209], v[82:83]
	v_pk_mul_f32 v[210:211], v[210:211], v[84:85]
	v_pk_add_f32 v[86:87], v[86:87], v[152:153]
	v_pk_add_f32 v[92:93], v[92:93], v[152:153]
	v_rcp_f32_e32 v86, v86
	v_rcp_f32_e32 v87, v87
	v_rcp_f32_e32 v92, v92
	v_rcp_f32_e32 v93, v93
	s_nop 0
	v_pk_mul_f32 v[208:209], v[208:209], v[86:87]
	v_pk_mul_f32 v[210:211], v[210:211], v[92:93]
	v_cvt_pk_bf16_f32 v82, v208, v209
	v_cvt_pk_bf16_f32 v83, v210, v211
	v_pk_fma_f32 v[208:209], v[22:23], v[204:205], v[230:231]
	v_pk_fma_f32 v[210:211], v[24:25], v[206:207], v[232:233]
	v_fmac_f32_dpp v208, v22, v246 row_shr:1 row_mask:0xf bank_mask:0xf
	v_fmac_f32_dpp v209, v23, v247 row_shr:1 row_mask:0xf bank_mask:0xf
	v_fmac_f32_dpp v210, v24, v248 row_shr:1 row_mask:0xf bank_mask:0xf
	v_fmac_f32_dpp v211, v25, v249 row_shr:1 row_mask:0xf bank_mask:0xf
	v_fmac_f32_dpp v208, v22, v238 row_shr:2 row_mask:0xf bank_mask:0xf
	v_fmac_f32_dpp v209, v23, v239 row_shr:2 row_mask:0xf bank_mask:0xf
	v_fmac_f32_dpp v210, v24, v240 row_shr:2 row_mask:0xf bank_mask:0xf
	v_fmac_f32_dpp v211, v25, v241 row_shr:2 row_mask:0xf bank_mask:0xf
	v_fmac_f32_dpp v208, v30, v108 row_ror:1 row_mask:0xf bank_mask:0xf
	v_fmac_f32_dpp v209, v31, v109 row_ror:1 row_mask:0xf bank_mask:0xf
	v_fmac_f32_dpp v210, v32, v110 row_ror:1 row_mask:0xf bank_mask:0xf
	v_fmac_f32_dpp v211, v33, v111 row_ror:1 row_mask:0xf bank_mask:0xf
	v_fmac_f32_dpp v208, v30, v116 row_ror:2 row_mask:0xf bank_mask:0xf
	v_fmac_f32_dpp v209, v31, v117 row_ror:2 row_mask:0xf bank_mask:0xf
	v_fmac_f32_dpp v210, v32, v118 row_ror:2 row_mask:0xf bank_mask:0xf
	v_fmac_f32_dpp v211, v33, v119 row_ror:2 row_mask:0xf bank_mask:0xf
	v_pk_mul_f32 v[86:87], v[208:209], v[208:209]
	v_pk_mul_f32 v[92:93], v[210:211], v[210:211]
	v_pk_fma_f32 v[86:87], v[86:87], s[42:43], v[154:155] op_sel_hi:[1,0,1]
	v_pk_fma_f32 v[92:93], v[92:93], s[42:43], v[154:155] op_sel_hi:[1,0,1]
	v_pk_mul_f32 v[86:87], v[208:209], v[86:87]
	v_pk_mul_f32 v[92:93], v[210:211], v[92:93]
	v_exp_f32_e32 v86, v86
	v_exp_f32_e32 v87, v87
	v_exp_f32_e32 v92, v92
	v_exp_f32_e32 v93, v93
	v_pk_mul_f32 v[208:209], v[208:209], v[18:19]
	v_pk_mul_f32 v[210:211], v[210:211], v[20:21]
	v_pk_add_f32 v[86:87], v[86:87], v[152:153]
	v_pk_add_f32 v[92:93], v[92:93], v[152:153]
	v_rcp_f32_e32 v86, v86
	v_rcp_f32_e32 v87, v87
	v_rcp_f32_e32 v92, v92
	v_rcp_f32_e32 v93, v93
;     __device__ __forceinline__ void operator()(const f32x4 (&acc)[2][2][4][2], const Unit& u, int wr, int wc, int fr, int fq) const {
;     ...
;                 for (int m = 0; m < 4; ++m) {
;                     const int r = row0 + ai * HALF + m * 16; const float rs = rstd[ai][m];
;                     const f32x4 a = acc[ai][0][m][n] * rs, b = acc[ai][1][m][n] * rs; f32x4 p1, p2;
;                     if (!smp) {
; #pragma unroll
;                         for (int e2 = 0; e2 < 4; ++e2) { const float s1 = fr == 15 ? pa[e2] : a[e2], s2 = fr >= 14 ? pa[e2] : a[e2]; p1[e2] = ror1(s1); p2[e2] = ror2(s2); }
;                         if (ai == 0 && wr == 0 && m == 0 && fr < 2) { *(f32x4*)(EA + ((size_t)u.pm * 4 + fr) * FF + j0 + 4 * n) = a; *(f32x4*)(EB + ((size_t)u.pm * 2 + fr) * FF + j0 + 4 * n) = b; }
;                         if (ai == 1 && wr == 1 && m == 3 && fr >= 14) { *(f32x4*)(EA + ((size_t)u.pm * 4 + 2 + (fr - 14)) * FF + j0 + 4 * n) = a;
;                             if ((u.pm & 7) == 7) *(f32x4*)(o_conv_p + ((size_t)(u.pm >> 3) * 2 + (fr - 14)) * FF + j0 + 4 * n) = a; }
;                     } else {
;                         const int t = fr & 7, bb = (r - 16384) >> 3;
; #pragma unroll
;                         for (int e2 = 0; e2 < 4; ++e2) { p1[e2] = ror1(a[e2]); p2[e2] = ror2(a[e2]); }
;                         if (t < 2) { const f32x4 h1 = *(const f32x4*)(state_conv + ((size_t)bb * 2 + 1) * FF + j0 + 4 * n);
;                             if (t == 0) { p1 = h1; p2 = *(const f32x4*)(state_conv + ((size_t)bb * 2) * FF + j0 + 4 * n); } else p2 = h1; }
;                         if (t >= 6) *(f32x4*)(o_conv_s + ((size_t)bb * 2 + (t - 6)) * FF + j0 + 4 * n) = a;
;                     }
;                     f32x4 hv;
; #pragma unroll
;                     for (int e2 = 0; e2 < 1; ++e2) {
;                         const f32x4 c4 = cb + w0 * p2 + w1 * p1 + w2 * a;
;                         const f32x4 z = c4 * ((c4 * c4) * (-0.10294324f) + (-2.3022082f));
;                         f32x4 den; den[0] = 1.f + __builtin_amdgcn_exp2f(z[0]); den[1] = 1.f + __builtin_amdgcn_exp2f(z[1]); den[2] = 1.f + __builtin_amdgcn_exp2f(z[2]); den[3] = 1.f + __builtin_amdgcn_exp2f(z[3]);
;                         f32x4 rc; rc[0] = frcp(den[0]); rc[1] = frcp(den[1]); rc[2] = frcp(den[2]); rc[3] = frcp(den[3]);
;                         hv = (c4 * rc) * b; }
	s_nop 0
	v_pk_mul_f32 v[208:209], v[208:209], v[86:87]
	v_pk_mul_f32 v[210:211], v[210:211], v[92:93]
	v_cvt_pk_bf16_f32 v84, v208, v209
	v_cvt_pk_bf16_f32 v85, v210, v211
	global_store_dwordx4 v212, v[82:85], s[80:81]
	s_add_u32 s80, s80, 0x16000
	s_addc_u32 s81, s81, 0
	v_pk_fma_f32 v[208:209], v[78:79], v[250:251], v[226:227]
	v_pk_fma_f32 v[210:211], v[80:81], v[252:253], v[228:229]
	v_fmac_f32_dpp v208, v78, v242 row_shr:1 row_mask:0xf bank_mask:0xf
	v_fmac_f32_dpp v209, v79, v243 row_shr:1 row_mask:0xf bank_mask:0xf
	v_fmac_f32_dpp v210, v80, v244 row_shr:1 row_mask:0xf bank_mask:0xf
	v_fmac_f32_dpp v211, v81, v245 row_shr:1 row_mask:0xf bank_mask:0xf
	v_fmac_f32_dpp v208, v78, v234 row_shr:2 row_mask:0xf bank_mask:0xf
	v_fmac_f32_dpp v209, v79, v235 row_shr:2 row_mask:0xf bank_mask:0xf
	v_fmac_f32_dpp v210, v80, v236 row_shr:2 row_mask:0xf bank_mask:0xf
	v_fmac_f32_dpp v211, v81, v237 row_shr:2 row_mask:0xf bank_mask:0xf
	v_fmac_f32_dpp v208, v88, v104 row_ror:1 row_mask:0xf bank_mask:0xf
	v_fmac_f32_dpp v209, v89, v105 row_ror:1 row_mask:0xf bank_mask:0xf
	v_fmac_f32_dpp v210, v90, v106 row_ror:1 row_mask:0xf bank_mask:0xf
	v_fmac_f32_dpp v211, v91, v107 row_ror:1 row_mask:0xf bank_mask:0xf
	v_fmac_f32_dpp v208, v88, v112 row_ror:2 row_mask:0xf bank_mask:0xf
	v_fmac_f32_dpp v209, v89, v113 row_ror:2 row_mask:0xf bank_mask:0xf
	v_fmac_f32_dpp v210, v90, v114 row_ror:2 row_mask:0xf bank_mask:0xf
	v_fmac_f32_dpp v211, v91, v115 row_ror:2 row_mask:0xf bank_mask:0xf
	v_pk_mul_f32 v[86:87], v[208:209], v[208:209]
	v_pk_mul_f32 v[92:93], v[210:211], v[210:211]
	v_pk_fma_f32 v[86:87], v[86:87], s[42:43], v[154:155] op_sel_hi:[1,0,1]
	v_pk_fma_f32 v[92:93], v[92:93], s[42:43], v[154:155] op_sel_hi:[1,0,1]
	v_pk_mul_f32 v[86:87], v[208:209], v[86:87]
	v_pk_mul_f32 v[92:93], v[210:211], v[92:93]
	v_exp_f32_e32 v86, v86
	v_exp_f32_e32 v87, v87
	v_exp_f32_e32 v92, v92
	v_exp_f32_e32 v93, v93
	v_pk_mul_f32 v[208:209], v[208:209], v[70:71]
	v_pk_mul_f32 v[210:211], v[210:211], v[72:73]
	v_pk_add_f32 v[86:87], v[86:87], v[152:153]
	v_pk_add_f32 v[92:93], v[92:93], v[152:153]
	v_rcp_f32_e32 v86, v86
	v_rcp_f32_e32 v87, v87
	v_rcp_f32_e32 v92, v92
	v_rcp_f32_e32 v93, v93
	s_nop 0
	v_pk_mul_f32 v[208:209], v[208:209], v[86:87]
	v_pk_mul_f32 v[210:211], v[210:211], v[92:93]
	v_cvt_pk_bf16_f32 v70, v208, v209
	v_cvt_pk_bf16_f32 v71, v210, v211
	v_pk_fma_f32 v[208:209], v[14:15], v[204:205], v[230:231]
	v_pk_fma_f32 v[210:211], v[16:17], v[206:207], v[232:233]
	v_fmac_f32_dpp v208, v14, v246 row_shr:1 row_mask:0xf bank_mask:0xf
	v_fmac_f32_dpp v209, v15, v247 row_shr:1 row_mask:0xf bank_mask:0xf
	v_fmac_f32_dpp v210, v16, v248 row_shr:1 row_mask:0xf bank_mask:0xf
	v_fmac_f32_dpp v211, v17, v249 row_shr:1 row_mask:0xf bank_mask:0xf
	v_fmac_f32_dpp v208, v14, v238 row_shr:2 row_mask:0xf bank_mask:0xf
	v_fmac_f32_dpp v209, v15, v239 row_shr:2 row_mask:0xf bank_mask:0xf
	v_fmac_f32_dpp v210, v16, v240 row_shr:2 row_mask:0xf bank_mask:0xf
	v_fmac_f32_dpp v211, v17, v241 row_shr:2 row_mask:0xf bank_mask:0xf
	v_fmac_f32_dpp v208, v22, v108 row_ror:1 row_mask:0xf bank_mask:0xf
	v_fmac_f32_dpp v209, v23, v109 row_ror:1 row_mask:0xf bank_mask:0xf
	v_fmac_f32_dpp v210, v24, v110 row_ror:1 row_mask:0xf bank_mask:0xf
	v_fmac_f32_dpp v211, v25, v111 row_ror:1 row_mask:0xf bank_mask:0xf
	v_fmac_f32_dpp v208, v22, v116 row_ror:2 row_mask:0xf bank_mask:0xf
	v_fmac_f32_dpp v209, v23, v117 row_ror:2 row_mask:0xf bank_mask:0xf
	v_fmac_f32_dpp v210, v24, v118 row_ror:2 row_mask:0xf bank_mask:0xf
	v_fmac_f32_dpp v211, v25, v119 row_ror:2 row_mask:0xf bank_mask:0xf
	v_pk_mul_f32 v[86:87], v[208:209], v[208:209]
	v_pk_mul_f32 v[92:93], v[210:211], v[210:211]
	v_pk_fma_f32 v[86:87], v[86:87], s[42:43], v[154:155] op_sel_hi:[1,0,1]
	v_pk_fma_f32 v[92:93], v[92:93], s[42:43], v[154:155] op_sel_hi:[1,0,1]
	v_pk_mul_f32 v[86:87], v[208:209], v[86:87]
	v_pk_mul_f32 v[92:93], v[210:211], v[92:93]
	v_exp_f32_e32 v86, v86
	v_exp_f32_e32 v87, v87
	v_exp_f32_e32 v92, v92
	v_exp_f32_e32 v93, v93
	v_pk_mul_f32 v[208:209], v[208:209], v[10:11]
	v_pk_mul_f32 v[210:211], v[210:211], v[12:13]
	v_pk_add_f32 v[86:87], v[86:87], v[152:153]
	v_pk_add_f32 v[92:93], v[92:93], v[152:153]
	v_rcp_f32_e32 v86, v86
	v_rcp_f32_e32 v87, v87
	v_rcp_f32_e32 v92, v92
	v_rcp_f32_e32 v93, v93
	s_nop 0
	v_pk_mul_f32 v[208:209], v[208:209], v[86:87]
	v_pk_mul_f32 v[210:211], v[210:211], v[92:93]
	v_cvt_pk_bf16_f32 v72, v208, v209
	v_cvt_pk_bf16_f32 v73, v210, v211
	global_store_dwordx4 v212, v[70:73], s[80:81]
	s_add_u32 s80, s80, 0x16000
	s_addc_u32 s81, s81, 0
	s_cmp_lg_u32 s71, 1
	s_cbranch_scc1 .Lepi5_noedge1
	v_add_u32_e32 v99, -14, v200
	s_movk_i32 s75, 0x2c00
	v_mad_u32_u24 v99, v99, s75, v213
	s_mul_i32 s73, s28, 0xb000
	s_add_u32 s73, s73, 0x5800
	s_add_u32 s88, s86, 0x4000000
	s_addc_u32 s89, s87, 0
	s_add_u32 s88, s88, s73
	s_addc_u32 s89, s89, 0
	s_mov_b64 exec, s[90:91]
	global_store_dwordx4 v99, v[74:77], s[88:89]
	global_store_dwordx4 v99, v[6:9], s[88:89] offset:16
	s_and_b32 s73, s28, 7
	s_cmp_lg_u32 s73, 7
	s_cbranch_scc1 .Lepi5_noconvp
	v_readlane_b32 s88, v254, 58
	v_readlane_b32 s89, v254, 59
	s_lshr_b32 s73, s28, 3
	s_mul_i32 s73, s73, 0x5800
	s_add_u32 s73, s73, 0x461e000
	s_nop 4
	s_add_u32 s88, s88, s73
	s_addc_u32 s89, s89, 0
	global_store_dwordx4 v99, v[74:77], s[88:89]
	global_store_dwordx4 v99, v[6:9], s[88:89] offset:16

; __device__ __forceinline__ unsigned cvt_pk_bf16(float lo, float hi) { unsigned r; asm volatile("v_cvt_pk_bf16_f32 %0, %1, %2" : "=v"(r) : "v"(lo), "v"(hi)); return r; }
; __device__ __forceinline__ float frcp(float x) { return __builtin_amdgcn_rcpf(x); }
;     __device__ __forceinline__ void operator()(const f32x4 (&acc)[2][2][4][2], const Unit& u, int wr, int wc, int fr, int fq) const {
;     ...
;                     f32x4 hv;
; #pragma unroll
;                     for (int e2 = 0; e2 < 1; ++e2) {
;                         const f32x4 c4 = cb + w0 * p2 + w1 * p1 + w2 * a;
;                         const f32x4 z = c4 * ((c4 * c4) * (-0.10294324f) + (-2.3022082f));
;                         f32x4 den; den[0] = 1.f + __builtin_amdgcn_exp2f(z[0]); den[1] = 1.f + __builtin_amdgcn_exp2f(z[1]); den[2] = 1.f + __builtin_amdgcn_exp2f(z[2]); den[3] = 1.f + __builtin_amdgcn_exp2f(z[3]);
;                         f32x4 rc; rc[0] = frcp(den[0]); rc[1] = frcp(den[1]); rc[2] = frcp(den[2]); rc[3] = frcp(den[3]);
;                         hv = (c4 * rc) * b; }
;                     const u32x2 pkv = (u32x2){cvt_pk_bf16(hv[0], hv[1]), cvt_pk_bf16(hv[2], hv[3])};
;                     if (n == 0) pk0[ai][m] = pkv; else *(u32x4*)(HID + (size_t)r * FF + j0) = (u32x4){pk0[ai][m][0], pk0[ai][m][1], pkv[0], pkv[1]};
;                     pa = a;
.Lepi5_noedge1:
	v_pk_fma_f32 v[208:209], v[74:75], v[250:251], v[226:227]
	v_pk_fma_f32 v[210:211], v[76:77], v[252:253], v[228:229]
	v_fmac_f32_dpp v208, v74, v242 row_shr:1 row_mask:0xf bank_mask:0xf
	v_fmac_f32_dpp v209, v75, v243 row_shr:1 row_mask:0xf bank_mask:0xf
	v_fmac_f32_dpp v210, v76, v244 row_shr:1 row_mask:0xf bank_mask:0xf
	v_fmac_f32_dpp v211, v77, v245 row_shr:1 row_mask:0xf bank_mask:0xf
	v_fmac_f32_dpp v208, v74, v234 row_shr:2 row_mask:0xf bank_mask:0xf
	v_fmac_f32_dpp v209, v75, v235 row_shr:2 row_mask:0xf bank_mask:0xf
	v_fmac_f32_dpp v210, v76, v236 row_shr:2 row_mask:0xf bank_mask:0xf
	v_fmac_f32_dpp v211, v77, v237 row_shr:2 row_mask:0xf bank_mask:0xf
	v_fmac_f32_dpp v208, v78, v104 row_ror:1 row_mask:0xf bank_mask:0xf
	v_fmac_f32_dpp v209, v79, v105 row_ror:1 row_mask:0xf bank_mask:0xf
	v_fmac_f32_dpp v210, v80, v106 row_ror:1 row_mask:0xf bank_mask:0xf
	v_fmac_f32_dpp v211, v81, v107 row_ror:1 row_mask:0xf bank_mask:0xf
	v_fmac_f32_dpp v208, v78, v112 row_ror:2 row_mask:0xf bank_mask:0xf
	v_fmac_f32_dpp v209, v79, v113 row_ror:2 row_mask:0xf bank_mask:0xf
	v_fmac_f32_dpp v210, v80, v114 row_ror:2 row_mask:0xf bank_mask:0xf
	v_fmac_f32_dpp v211, v81, v115 row_ror:2 row_mask:0xf bank_mask:0xf
	v_pk_mul_f32 v[86:87], v[208:209], v[208:209]
	v_pk_mul_f32 v[92:93], v[210:211], v[210:211]
	v_pk_fma_f32 v[86:87], v[86:87], s[42:43], v[154:155] op_sel_hi:[1,0,1]
	v_pk_fma_f32 v[92:93], v[92:93], s[42:43], v[154:155] op_sel_hi:[1,0,1]
	v_pk_mul_f32 v[86:87], v[208:209], v[86:87]
	v_pk_mul_f32 v[92:93], v[210:211], v[92:93]
	v_exp_f32_e32 v86, v86
	v_exp_f32_e32 v87, v87
	v_exp_f32_e32 v92, v92
	v_exp_f32_e32 v93, v93
	v_pk_mul_f32 v[208:209], v[208:209], v[66:67]
	v_pk_mul_f32 v[210:211], v[210:211], v[68:69]
	v_pk_add_f32 v[86:87], v[86:87], v[152:153]
	v_pk_add_f32 v[92:93], v[92:93], v[152:153]
	v_rcp_f32_e32 v86, v86
	v_rcp_f32_e32 v87, v87
	v_rcp_f32_e32 v92, v92
	v_rcp_f32_e32 v93, v93
	s_nop 0
	v_pk_mul_f32 v[208:209], v[208:209], v[86:87]
	v_pk_mul_f32 v[210:211], v[210:211], v[92:93]
	v_cvt_pk_bf16_f32 v66, v208, v209
	v_cvt_pk_bf16_f32 v67, v210, v211
	v_pk_fma_f32 v[208:209], v[6:7], v[204:205], v[230:231]
	v_pk_fma_f32 v[210:211], v[8:9], v[206:207], v[232:233]
	v_fmac_f32_dpp v208, v6, v246 row_shr:1 row_mask:0xf bank_mask:0xf
	v_fmac_f32_dpp v209, v7, v247 row_shr:1 row_mask:0xf bank_mask:0xf
	v_fmac_f32_dpp v210, v8, v248 row_shr:1 row_mask:0xf bank_mask:0xf
	v_fmac_f32_dpp v211, v9, v249 row_shr:1 row_mask:0xf bank_mask:0xf
	v_fmac_f32_dpp v208, v6, v238 row_shr:2 row_mask:0xf bank_mask:0xf
	v_fmac_f32_dpp v209, v7, v239 row_shr:2 row_mask:0xf bank_mask:0xf
	v_fmac_f32_dpp v210, v8, v240 row_shr:2 row_mask:0xf bank_mask:0xf
	v_fmac_f32_dpp v211, v9, v241 row_shr:2 row_mask:0xf bank_mask:0xf
	v_fmac_f32_dpp v208, v14, v108 row_ror:1 row_mask:0xf bank_mask:0xf
	v_fmac_f32_dpp v209, v15, v109 row_ror:1 row_mask:0xf bank_mask:0xf
	v_fmac_f32_dpp v210, v16, v110 row_ror:1 row_mask:0xf bank_mask:0xf
	v_fmac_f32_dpp v211, v17, v111 row_ror:1 row_mask:0xf bank_mask:0xf
	v_fmac_f32_dpp v208, v14, v116 row_ror:2 row_mask:0xf bank_mask:0xf
	v_fmac_f32_dpp v209, v15, v117 row_ror:2 row_mask:0xf bank_mask:0xf
	v_fmac_f32_dpp v210, v16, v118 row_ror:2 row_mask:0xf bank_mask:0xf
	v_fmac_f32_dpp v211, v17, v119 row_ror:2 row_mask:0xf bank_mask:0xf
	v_pk_mul_f32 v[86:87], v[208:209], v[208:209]
	v_pk_mul_f32 v[92:93], v[210:211], v[210:211]
	v_pk_fma_f32 v[86:87], v[86:87], s[42:43], v[154:155] op_sel_hi:[1,0,1]
	v_pk_fma_f32 v[92:93], v[92:93], s[42:43], v[154:155] op_sel_hi:[1,0,1]
	v_pk_mul_f32 v[86:87], v[208:209], v[86:87]
	v_pk_mul_f32 v[92:93], v[210:211], v[92:93]
	v_exp_f32_e32 v86, v86
	v_exp_f32_e32 v87, v87
	v_exp_f32_e32 v92, v92
	v_exp_f32_e32 v93, v93
	v_pk_mul_f32 v[208:209], v[208:209], v[2:3]
	v_pk_mul_f32 v[210:211], v[210:211], v[4:5]
	v_pk_add_f32 v[86:87], v[86:87], v[152:153]
	v_pk_add_f32 v[92:93], v[92:93], v[152:153]
	v_rcp_f32_e32 v86, v86
	v_rcp_f32_e32 v87, v87
	v_rcp_f32_e32 v92, v92
	v_rcp_f32_e32 v93, v93
	s_nop 0
	v_pk_mul_f32 v[208:209], v[208:209], v[86:87]
	v_pk_mul_f32 v[210:211], v[210:211], v[92:93]
	v_cvt_pk_bf16_f32 v68, v208, v209
	v_cvt_pk_bf16_f32 v69, v210, v211
	global_store_dwordx4 v212, v[66:69], s[80:81]
	s_branch .Lepi5_done
; #define PG8_LAS __attribute__((address_space(3)))
;     __device__ __forceinline__ void operator()(const f32x4 (&acc)[2][2][4][2], const Unit& u, int wr, int wc, int fr, int fq) const {
;     ...
;         float rstd[2][4];
; #pragma unroll
;         for (int ai = 0; ai < 2; ++ai)
; #pragma unroll
;             for (int m = 0; m < 4; ++m) rstd[ai][m] = RSTD[u.idx * 256 + ai * HALF + wr * 64 + m * 16 + fr];
;         if (!smp) {
;             if (fr >= 14) {
; #pragma unroll
;                 for (int ai = 0; ai < 2; ++ai)
; #pragma unroll
;                     for (int n = 0; n < 2; ++n) *(PG8_LAS f32x4*)(xch + ((((ai * 2 + wr) * 4 + wc) * 4 + fq) * 2 + (fr - 14)) * 8 + 4 * n) = acc[ai][0][3][n] * rstd[ai][3]; }
;             asm volatile("s_waitcnt lgkmcnt(0)" ::: "memory"); __builtin_amdgcn_s_barrier(); asm volatile("" ::: "memory");
;         }
;     ...
;         asm volatile("s_waitcnt vmcnt(0)" ::: "memory");
;         if (blockIdx.x == 0 && threadIdx.x == 0) ((volatile PG8_LAS unsigned long long*)((PG8_LAS unsigned char*)xch - 4096 + 512))[43] += __builtin_amdgcn_s_memrealtime() - pu_t0;
;     ...
;         auto ror1 = [](float v) -> float { return __builtin_bit_cast(float, __builtin_amdgcn_mov_dpp(__builtin_bit_cast(int, v), 0x121, 0xf, 0xf, true)); };
;         auto ror2 = [](float v) -> float { return __builtin_bit_cast(float, __builtin_amdgcn_mov_dpp(__builtin_bit_cast(int, v), 0x122, 0xf, 0xf, true)); };
;         u32x2 pk0[2][4];
; #pragma unroll
;         for (int n = 0; n < 2; ++n) {
;             const f32x4 cb = *(const f32x4*)(conv_b + j0 + 4 * n), w0 = *(const f32x4*)(conv_w + j0 + 4 * n), w1 = *(const f32x4*)(conv_w + FF + j0 + 4 * n), w2 = *(const f32x4*)(conv_w + 2 * FF + j0 + 4 * n);
; #pragma unroll
;             for (int ai = 0; ai < 2; ++ai) {
;                 f32x4 pa = (f32x4){0.f, 0.f, 0.f, 0.f};
;                 if (!smp && fr >= 14 && (wr == 1 || ai == 1)) { const int sai = wr == 1 ? ai : 0, swr = wr == 1 ? 0 : 1;
;                     pa = *(const PG8_LAS f32x4*)(xch + ((((sai * 2 + swr) * 4 + wc) * 4 + fq) * 2 + (fr - 14)) * 8 + 4 * n); }
; #pragma unroll
;                 for (int m = 0; m < 4; ++m) {
;                     const int r = row0 + ai * HALF + m * 16; const float rs = rstd[ai][m];
;                     const f32x4 a = acc[ai][0][m][n] * rs, b = acc[ai][1][m][n] * rs; f32x4 p1, p2;
;                     if (!smp) {
; #pragma unroll
.Lepi5_smp:
	v_readfirstlane_b32 s70, v0
	v_readlane_b32 s82, v254, 13
	v_readlane_b32 s83, v254, 14
	v_readlane_b32 s86, v254, 19
	v_readlane_b32 s87, v254, 20
	v_readlane_b32 s88, v254, 58
	v_readlane_b32 s89, v254, 59
	v_and_b32_e32 v200, 15, v202
	v_lshrrev_b32_e32 v87, 4, v202
	v_and_b32_e32 v201, 7, v202
	v_and_b32_e32 v92, 1, v202
	s_nop 0
	v_cmp_eq_u32_e64 s[90:91], 0, v201
	v_cmp_gt_u32_e64 s[94:95], 2, v201
	v_cmp_lt_u32_e64 s[84:85], 5, v201
	v_cmp_eq_u32_e64 s[92:93], 1, v92
	s_lshr_b32 s70, s70, 6
	s_lshr_b32 s71, s70, 2
	s_and_b32 s72, s70, 3
	s_sub_u32 s86, s86, 0x4000
	s_subb_u32 s87, s87, 0
	s_lshl_b32 s73, s10, 7
	s_lshl_b32 s74, s72, 5
	s_add_i32 s73, s73, s74
	v_lshl_add_u32 v213, v87, 3, s73
	v_lshlrev_b32_e32 v213, 2, v213
	v_and_b32_e32 v99, 6, v200
	v_lshrrev_b32_e32 v86, 3, v200
	v_add_u32_e32 v99, v99, v86
	v_lshlrev_b32_e32 v99, 1, v99
	v_sub_u32_e32 v93, 1, v92
	v_add_u32_e32 v99, v99, v93
	s_movk_i32 s75, 0x2c00
	v_mad_u32_u24 v99, v99, s75, v213
	s_sub_u32 s73, s28, 64
	s_lshl_b32 s73, s73, 5
	s_lshl_b32 s74, s71, 3
	s_add_i32 s73, s73, s74
	s_mul_i32 s73, s73, 0x5800
	s_add_u32 s82, s82, s73
	s_addc_u32 s83, s83, 0
	s_add_u32 s34, s82, 0x58000
	s_addc_u32 s35, s83, 0
	global_load_dwordx4 v[188:191], v99, s[82:83]
	global_load_dwordx4 v[192:195], v99, s[82:83] offset:16
	global_load_dwordx4 v[196:199], v99, s[34:35]
	global_load_dwordx4 v[160:163], v99, s[34:35] offset:16
	s_lshl_b32 s75, s11, 10
	s_lshl_b32 s74, s71, 8
	s_add_i32 s75, s75, s74
	s_add_i32 s75, s75, 0x22000
	v_lshl_add_u32 v86, v200, 2, s75
	ds_read2_b32 v[152:153], v86 offset1:16
	ds_read2_b32 v[154:155], v86 offset0:32 offset1:48
	ds_read2_b32 v[156:157], v86 offset0:128 offset1:144
	ds_read2_b32 v[158:159], v86 offset0:160 offset1:176
	s_and_b32 s75, s11, 1
	s_lshl_b32 s75, s75, 11
	s_add_i32 s75, s75, 0x24000
	s_lshl_b32 s74, s72, 7
	s_add_i32 s75, s75, s74
	v_lshl_add_u32 v86, v87, 5, s75
	ds_read_b128 v[226:229], v86 offset:0
	ds_read_b128 v[230:233], v86 offset:16
	ds_read_b128 v[234:237], v86 offset:512
	ds_read_b128 v[238:241], v86 offset:528
	ds_read_b128 v[242:245], v86 offset:1024
	ds_read_b128 v[246:249], v86 offset:1040
	ds_read_b128 v[250:253], v86 offset:1536
	ds_read_b128 v[204:207], v86 offset:1552
	s_mul_i32 s74, s71, 0x58000
	v_lshrrev_b32_e32 v212, 1, v213
	v_add_u32_e32 v212, s74, v212
	s_movk_i32 s75, 0x1600
	v_mad_u32_u24 v212, v200, s75, v212
	v_lshrrev_b32_e32 v98, 3, v200
	v_lshl_add_u32 v98, v98, 1, v201
	v_add_u32_e32 v98, -6, v98
	s_movk_i32 s75, 0x2c00
	v_mad_u32_u24 v98, v98, s75, v213
	s_add_u32 s88, s88, 0x6c2a000
	s_addc_u32 s89, s89, 0
	s_add_u32 s42, s88, s73
	s_addc_u32 s43, s89, 0
	s_mul_i32 s73, s28, 0x160000
	s_add_u32 s80, s86, 0x9e00000
	s_addc_u32 s81, s87, 0
	s_add_u32 s80, s80, s73
	s_addc_u32 s81, s81, 0
	s_waitcnt lgkmcnt(0)
	v_pk_mul_f32 v[148:149], v[148:149], v[152:153] op_sel_hi:[1,0]
	v_pk_mul_f32 v[150:151], v[150:151], v[152:153] op_sel_hi:[1,0]
	v_pk_mul_f32 v[62:63], v[62:63], v[152:153] op_sel_hi:[1,0]
	v_pk_mul_f32 v[64:65], v[64:65], v[152:153] op_sel_hi:[1,0]
	v_pk_mul_f32 v[144:145], v[144:145], v[152:153] op_sel_hi:[1,0]
	v_pk_mul_f32 v[146:147], v[146:147], v[152:153] op_sel_hi:[1,0]
	v_pk_mul_f32 v[58:59], v[58:59], v[152:153] op_sel_hi:[1,0]
	v_pk_mul_f32 v[60:61], v[60:61], v[152:153] op_sel_hi:[1,0]
	v_pk_mul_f32 v[140:141], v[140:141], v[152:153] op_sel:[0,1] op_sel_hi:[1,1]
	v_pk_mul_f32 v[142:143], v[142:143], v[152:153] op_sel:[0,1] op_sel_hi:[1,1]
	v_pk_mul_f32 v[54:55], v[54:55], v[152:153] op_sel:[0,1] op_sel_hi:[1,1]
	v_pk_mul_f32 v[56:57], v[56:57], v[152:153] op_sel:[0,1] op_sel_hi:[1,1]
	v_pk_mul_f32 v[136:137], v[136:137], v[152:153] op_sel:[0,1] op_sel_hi:[1,1]
	v_pk_mul_f32 v[138:139], v[138:139], v[152:153] op_sel:[0,1] op_sel_hi:[1,1]
	v_pk_mul_f32 v[50:51], v[50:51], v[152:153] op_sel:[0,1] op_sel_hi:[1,1]
	v_pk_mul_f32 v[52:53], v[52:53], v[152:153] op_sel:[0,1] op_sel_hi:[1,1]
	v_pk_mul_f32 v[132:133], v[132:133], v[154:155] op_sel_hi:[1,0]
	v_pk_mul_f32 v[134:135], v[134:135], v[154:155] op_sel_hi:[1,0]
	v_pk_mul_f32 v[46:47], v[46:47], v[154:155] op_sel_hi:[1,0]
	v_pk_mul_f32 v[48:49], v[48:49], v[154:155] op_sel_hi:[1,0]
	v_pk_mul_f32 v[128:129], v[128:129], v[154:155] op_sel_hi:[1,0]
	v_pk_mul_f32 v[130:131], v[130:131], v[154:155] op_sel_hi:[1,0]
	v_pk_mul_f32 v[42:43], v[42:43], v[154:155] op_sel_hi:[1,0]
	v_pk_mul_f32 v[44:45], v[44:45], v[154:155] op_sel_hi:[1,0]
	v_pk_mul_f32 v[124:125], v[124:125], v[154:155] op_sel:[0,1] op_sel_hi:[1,1]
	v_pk_mul_f32 v[126:127], v[126:127], v[154:155] op_sel:[0,1] op_sel_hi:[1,1]
	v_pk_mul_f32 v[38:39], v[38:39], v[154:155] op_sel:[0,1] op_sel_hi:[1,1]
	v_pk_mul_f32 v[40:41], v[40:41], v[154:155] op_sel:[0,1] op_sel_hi:[1,1]
	v_pk_mul_f32 v[94:95], v[94:95], v[154:155] op_sel:[0,1] op_sel_hi:[1,1]
	v_pk_mul_f32 v[96:97], v[96:97], v[154:155] op_sel:[0,1] op_sel_hi:[1,1]
	v_pk_mul_f32 v[34:35], v[34:35], v[154:155] op_sel:[0,1] op_sel_hi:[1,1]
	v_pk_mul_f32 v[36:37], v[36:37], v[154:155] op_sel:[0,1] op_sel_hi:[1,1]
	v_pk_mul_f32 v[120:121], v[120:121], v[156:157] op_sel_hi:[1,0]
	v_pk_mul_f32 v[122:123], v[122:123], v[156:157] op_sel_hi:[1,0]
	v_pk_mul_f32 v[30:31], v[30:31], v[156:157] op_sel_hi:[1,0]
	v_pk_mul_f32 v[32:33], v[32:33], v[156:157] op_sel_hi:[1,0]
	v_pk_mul_f32 v[100:101], v[100:101], v[156:157] op_sel_hi:[1,0]
	v_pk_mul_f32 v[102:103], v[102:103], v[156:157] op_sel_hi:[1,0]
	v_pk_mul_f32 v[26:27], v[26:27], v[156:157] op_sel_hi:[1,0]
	v_pk_mul_f32 v[28:29], v[28:29], v[156:157] op_sel_hi:[1,0]
	v_pk_mul_f32 v[88:89], v[88:89], v[156:157] op_sel:[0,1] op_sel_hi:[1,1]
;     __device__ __forceinline__ void operator()(const f32x4 (&acc)[2][2][4][2], const Unit& u, int wr, int wc, int fr, int fq) const {
;     ...
;                 for (int m = 0; m < 4; ++m) {
;                     const int r = row0 + ai * HALF + m * 16; const float rs = rstd[ai][m];
;                     const f32x4 a = acc[ai][0][m][n] * rs, b = acc[ai][1][m][n] * rs; f32x4 p1, p2;
;                     if (!smp) {
; #pragma unroll
;                         for (int e2 = 0; e2 < 4; ++e2) { const float s1 = fr == 15 ? pa[e2] : a[e2], s2 = fr >= 14 ? pa[e2] : a[e2]; p1[e2] = ror1(s1); p2[e2] = ror2(s2); }
;                         if (ai == 0 && wr == 0 && m == 0 && fr < 2) { *(f32x4*)(EA + ((size_t)u.pm * 4 + fr) * FF + j0 + 4 * n) = a; *(f32x4*)(EB + ((size_t)u.pm * 2 + fr) * FF + j0 + 4 * n) = b; }
;                         if (ai == 1 && wr == 1 && m == 3 && fr >= 14) { *(f32x4*)(EA + ((size_t)u.pm * 4 + 2 + (fr - 14)) * FF + j0 + 4 * n) = a;
;                             if ((u.pm & 7) == 7) *(f32x4*)(o_conv_p + ((size_t)(u.pm >> 3) * 2 + (fr - 14)) * FF + j0 + 4 * n) = a; }
;                     } else {
;                         const int t = fr & 7, bb = (r - 16384) >> 3;
; #pragma unroll
;                         for (int e2 = 0; e2 < 4; ++e2) { p1[e2] = ror1(a[e2]); p2[e2] = ror2(a[e2]); }
;                         if (t < 2) { const f32x4 h1 = *(const f32x4*)(state_conv + ((size_t)bb * 2 + 1) * FF + j0 + 4 * n);
;                             if (t == 0) { p1 = h1; p2 = *(const f32x4*)(state_conv + ((size_t)bb * 2) * FF + j0 + 4 * n); } else p2 = h1; }
;                         if (t >= 6) *(f32x4*)(o_conv_s + ((size_t)bb * 2 + (t - 6)) * FF + j0 + 4 * n) = a;
;                     }
	v_pk_mul_f32 v[90:91], v[90:91], v[156:157] op_sel:[0,1] op_sel_hi:[1,1]
	v_pk_mul_f32 v[22:23], v[22:23], v[156:157] op_sel:[0,1] op_sel_hi:[1,1]
	v_pk_mul_f32 v[24:25], v[24:25], v[156:157] op_sel:[0,1] op_sel_hi:[1,1]
	v_pk_mul_f32 v[82:83], v[82:83], v[156:157] op_sel:[0,1] op_sel_hi:[1,1]
	v_pk_mul_f32 v[84:85], v[84:85], v[156:157] op_sel:[0,1] op_sel_hi:[1,1]
	v_pk_mul_f32 v[18:19], v[18:19], v[156:157] op_sel:[0,1] op_sel_hi:[1,1]
	v_pk_mul_f32 v[20:21], v[20:21], v[156:157] op_sel:[0,1] op_sel_hi:[1,1]
	v_pk_mul_f32 v[78:79], v[78:79], v[158:159] op_sel_hi:[1,0]
	v_pk_mul_f32 v[80:81], v[80:81], v[158:159] op_sel_hi:[1,0]
	v_pk_mul_f32 v[14:15], v[14:15], v[158:159] op_sel_hi:[1,0]
	v_pk_mul_f32 v[16:17], v[16:17], v[158:159] op_sel_hi:[1,0]
	v_pk_mul_f32 v[70:71], v[70:71], v[158:159] op_sel_hi:[1,0]
	v_pk_mul_f32 v[72:73], v[72:73], v[158:159] op_sel_hi:[1,0]
	v_pk_mul_f32 v[10:11], v[10:11], v[158:159] op_sel_hi:[1,0]
	v_pk_mul_f32 v[12:13], v[12:13], v[158:159] op_sel_hi:[1,0]
	v_pk_mul_f32 v[74:75], v[74:75], v[158:159] op_sel:[0,1] op_sel_hi:[1,1]
	v_pk_mul_f32 v[76:77], v[76:77], v[158:159] op_sel:[0,1] op_sel_hi:[1,1]
	v_pk_mul_f32 v[6:7], v[6:7], v[158:159] op_sel:[0,1] op_sel_hi:[1,1]
	v_pk_mul_f32 v[8:9], v[8:9], v[158:159] op_sel:[0,1] op_sel_hi:[1,1]
	v_pk_mul_f32 v[66:67], v[66:67], v[158:159] op_sel:[0,1] op_sel_hi:[1,1]
	v_pk_mul_f32 v[68:69], v[68:69], v[158:159] op_sel:[0,1] op_sel_hi:[1,1]
	v_pk_mul_f32 v[2:3], v[2:3], v[158:159] op_sel:[0,1] op_sel_hi:[1,1]
	v_pk_mul_f32 v[4:5], v[4:5], v[158:159] op_sel:[0,1] op_sel_hi:[1,1]
	v_mov_b32_e32 v154, 0xc0135761
	v_mov_b32_e32 v155, 0xc0135761
	v_mov_b32_e32 v152, 1.0
	v_mov_b32_e32 v153, 1.0
	s_mov_b32 s74, 0xbdd2d3e8
	s_mov_b32 s75, 0xbdd2d3e8
	v_cndmask_b32_e64 v200, 0, 1.0, s[94:95]
	s_waitcnt vmcnt(0)
	v_cndmask_b32_e64 v86, v242, 0, s[92:93]
	v_cndmask_b32_e64 v208, v234, 0, s[92:93]
	v_cndmask_b32_e64 v156, 0, v234, s[92:93]
	v_cndmask_b32_e64 v87, v243, 0, s[92:93]
	v_cndmask_b32_e64 v209, v235, 0, s[92:93]
	v_cndmask_b32_e64 v157, 0, v235, s[92:93]
	v_cndmask_b32_e64 v92, v244, 0, s[92:93]
	v_cndmask_b32_e64 v210, v236, 0, s[92:93]
	v_cndmask_b32_e64 v158, 0, v236, s[92:93]
	v_cndmask_b32_e64 v93, v245, 0, s[92:93]
	v_cndmask_b32_e64 v211, v237, 0, s[92:93]
	v_cndmask_b32_e64 v159, 0, v237, s[92:93]
	v_mul_f32_e32 v104, v188, v86
	v_mul_f32_e32 v105, v189, v87
	v_mul_f32_e32 v106, v190, v92
	v_mul_f32_e32 v107, v191, v93
	v_fmac_f32_dpp v104, v188, v208 row_shl:1 row_mask:0xf bank_mask:0xf
	v_fmac_f32_dpp v105, v189, v209 row_shl:1 row_mask:0xf bank_mask:0xf
	v_fmac_f32_dpp v106, v190, v210 row_shl:1 row_mask:0xf bank_mask:0xf
	v_fmac_f32_dpp v107, v191, v211 row_shl:1 row_mask:0xf bank_mask:0xf
	v_fmac_f32_dpp v104, v188, v156 row_shr:1 row_mask:0xf bank_mask:0xf
	v_fmac_f32_dpp v105, v189, v157 row_shr:1 row_mask:0xf bank_mask:0xf
	v_fmac_f32_dpp v106, v190, v158 row_shr:1 row_mask:0xf bank_mask:0xf
	v_fmac_f32_dpp v107, v191, v159 row_shr:1 row_mask:0xf bank_mask:0xf
	v_mul_f32_e32 v112, v196, v86
	v_mul_f32_e32 v113, v197, v87
	v_mul_f32_e32 v114, v198, v92
	v_mul_f32_e32 v115, v199, v93
	v_fmac_f32_dpp v112, v196, v208 row_shl:1 row_mask:0xf bank_mask:0xf
	v_fmac_f32_dpp v113, v197, v209 row_shl:1 row_mask:0xf bank_mask:0xf
	v_fmac_f32_dpp v114, v198, v210 row_shl:1 row_mask:0xf bank_mask:0xf
	v_fmac_f32_dpp v115, v199, v211 row_shl:1 row_mask:0xf bank_mask:0xf
	v_fmac_f32_dpp v112, v196, v156 row_shr:1 row_mask:0xf bank_mask:0xf
	v_fmac_f32_dpp v113, v197, v157 row_shr:1 row_mask:0xf bank_mask:0xf
	v_fmac_f32_dpp v114, v198, v158 row_shr:1 row_mask:0xf bank_mask:0xf
	v_fmac_f32_dpp v115, v199, v159 row_shr:1 row_mask:0xf bank_mask:0xf
	v_cndmask_b32_e64 v86, v246, 0, s[92:93]
	v_cndmask_b32_e64 v208, v238, 0, s[92:93]
	v_cndmask_b32_e64 v156, 0, v238, s[92:93]
	v_cndmask_b32_e64 v87, v247, 0, s[92:93]
	v_cndmask_b32_e64 v209, v239, 0, s[92:93]
	v_cndmask_b32_e64 v157, 0, v239, s[92:93]
	v_cndmask_b32_e64 v92, v248, 0, s[92:93]
	v_cndmask_b32_e64 v210, v240, 0, s[92:93]
	v_cndmask_b32_e64 v158, 0, v240, s[92:93]
	v_cndmask_b32_e64 v93, v249, 0, s[92:93]
	v_cndmask_b32_e64 v211, v241, 0, s[92:93]
	v_cndmask_b32_e64 v159, 0, v241, s[92:93]
	v_mul_f32_e32 v108, v192, v86
	v_mul_f32_e32 v109, v193, v87
	v_mul_f32_e32 v110, v194, v92
	v_mul_f32_e32 v111, v195, v93
	v_fmac_f32_dpp v108, v192, v208 row_shl:1 row_mask:0xf bank_mask:0xf
	v_fmac_f32_dpp v109, v193, v209 row_shl:1 row_mask:0xf bank_mask:0xf
	v_fmac_f32_dpp v110, v194, v210 row_shl:1 row_mask:0xf bank_mask:0xf
	v_fmac_f32_dpp v111, v195, v211 row_shl:1 row_mask:0xf bank_mask:0xf
	v_fmac_f32_dpp v108, v192, v156 row_shr:1 row_mask:0xf bank_mask:0xf
	v_fmac_f32_dpp v109, v193, v157 row_shr:1 row_mask:0xf bank_mask:0xf
	v_fmac_f32_dpp v110, v194, v158 row_shr:1 row_mask:0xf bank_mask:0xf
	v_fmac_f32_dpp v111, v195, v159 row_shr:1 row_mask:0xf bank_mask:0xf
	v_mul_f32_e32 v116, v160, v86
	v_mul_f32_e32 v117, v161, v87
	v_mul_f32_e32 v118, v162, v92
	v_mul_f32_e32 v119, v163, v93
	v_fmac_f32_dpp v116, v160, v208 row_shl:1 row_mask:0xf bank_mask:0xf
	v_fmac_f32_dpp v117, v161, v209 row_shl:1 row_mask:0xf bank_mask:0xf
	v_fmac_f32_dpp v118, v162, v210 row_shl:1 row_mask:0xf bank_mask:0xf
	v_fmac_f32_dpp v119, v163, v211 row_shl:1 row_mask:0xf bank_mask:0xf
	v_fmac_f32_dpp v116, v160, v156 row_shr:1 row_mask:0xf bank_mask:0xf
	v_fmac_f32_dpp v117, v161, v157 row_shr:1 row_mask:0xf bank_mask:0xf
	v_fmac_f32_dpp v118, v162, v158 row_shr:1 row_mask:0xf bank_mask:0xf
	v_fmac_f32_dpp v119, v163, v159 row_shr:1 row_mask:0xf bank_mask:0xf
	v_cndmask_b32_e64 v242, v242, 0, s[90:91]
	v_cndmask_b32_e64 v234, v234, 0, s[94:95]
; __device__ __forceinline__ unsigned cvt_pk_bf16(float lo, float hi) { unsigned r; asm volatile("v_cvt_pk_bf16_f32 %0, %1, %2" : "=v"(r) : "v"(lo), "v"(hi)); return r; }
; __device__ __forceinline__ float frcp(float x) { return __builtin_amdgcn_rcpf(x); }
;     __device__ __forceinline__ void operator()(const f32x4 (&acc)[2][2][4][2], const Unit& u, int wr, int wc, int fr, int fq) const {
;     ...
;                     } else {
;                         const int t = fr & 7, bb = (r - 16384) >> 3;
; #pragma unroll
;                         for (int e2 = 0; e2 < 4; ++e2) { p1[e2] = ror1(a[e2]); p2[e2] = ror2(a[e2]); }
;                         if (t < 2) { const f32x4 h1 = *(const f32x4*)(state_conv + ((size_t)bb * 2 + 1) * FF + j0 + 4 * n);
;                             if (t == 0) { p1 = h1; p2 = *(const f32x4*)(state_conv + ((size_t)bb * 2) * FF + j0 + 4 * n); } else p2 = h1; }
;                         if (t >= 6) *(f32x4*)(o_conv_s + ((size_t)bb * 2 + (t - 6)) * FF + j0 + 4 * n) = a;
;                     }
;                     f32x4 hv;
; #pragma unroll
;                     for (int e2 = 0; e2 < 1; ++e2) {
;                         const f32x4 c4 = cb + w0 * p2 + w1 * p1 + w2 * a;
;                         const f32x4 z = c4 * ((c4 * c4) * (-0.10294324f) + (-2.3022082f));
;                         f32x4 den; den[0] = 1.f + __builtin_amdgcn_exp2f(z[0]); den[1] = 1.f + __builtin_amdgcn_exp2f(z[1]); den[2] = 1.f + __builtin_amdgcn_exp2f(z[2]); den[3] = 1.f + __builtin_amdgcn_exp2f(z[3]);
;                         f32x4 rc; rc[0] = frcp(den[0]); rc[1] = frcp(den[1]); rc[2] = frcp(den[2]); rc[3] = frcp(den[3]);
;                         hv = (c4 * rc) * b; }
;                     const u32x2 pkv = (u32x2){cvt_pk_bf16(hv[0], hv[1]), cvt_pk_bf16(hv[2], hv[3])};
;                     if (n == 0) pk0[ai][m] = pkv; else *(u32x4*)(HID + (size_t)r * FF + j0) = (u32x4){pk0[ai][m][0], pk0[ai][m][1], pkv[0], pkv[1]};
	v_cndmask_b32_e64 v243, v243, 0, s[90:91]
	v_cndmask_b32_e64 v235, v235, 0, s[94:95]
	v_cndmask_b32_e64 v244, v244, 0, s[90:91]
	v_cndmask_b32_e64 v236, v236, 0, s[94:95]
	v_cndmask_b32_e64 v245, v245, 0, s[90:91]
	v_cndmask_b32_e64 v237, v237, 0, s[94:95]
	v_cndmask_b32_e64 v246, v246, 0, s[90:91]
	v_cndmask_b32_e64 v238, v238, 0, s[94:95]
	v_cndmask_b32_e64 v247, v247, 0, s[90:91]
	v_cndmask_b32_e64 v239, v239, 0, s[94:95]
	v_cndmask_b32_e64 v248, v248, 0, s[90:91]
	v_cndmask_b32_e64 v240, v240, 0, s[94:95]
	v_cndmask_b32_e64 v249, v249, 0, s[90:91]
	v_cndmask_b32_e64 v241, v241, 0, s[94:95]
	v_pk_fma_f32 v[208:209], v[148:149], v[250:251], v[226:227]
	v_pk_fma_f32 v[210:211], v[150:151], v[252:253], v[228:229]
	v_fmac_f32_dpp v208, v148, v242 row_shr:1 row_mask:0xf bank_mask:0xf
	v_fmac_f32_dpp v209, v149, v243 row_shr:1 row_mask:0xf bank_mask:0xf
	v_fmac_f32_dpp v210, v150, v244 row_shr:1 row_mask:0xf bank_mask:0xf
	v_fmac_f32_dpp v211, v151, v245 row_shr:1 row_mask:0xf bank_mask:0xf
	v_fmac_f32_dpp v208, v148, v234 row_shr:2 row_mask:0xf bank_mask:0xf
	v_fmac_f32_dpp v209, v149, v235 row_shr:2 row_mask:0xf bank_mask:0xf
	v_fmac_f32_dpp v210, v150, v236 row_shr:2 row_mask:0xf bank_mask:0xf
	v_fmac_f32_dpp v211, v151, v237 row_shr:2 row_mask:0xf bank_mask:0xf
	v_fmac_f32_e32 v208, v104, v200
	v_fmac_f32_e32 v209, v105, v200
	v_fmac_f32_e32 v210, v106, v200
	v_fmac_f32_e32 v211, v107, v200
	v_pk_mul_f32 v[86:87], v[208:209], v[208:209]
	v_pk_mul_f32 v[92:93], v[210:211], v[210:211]
	v_pk_fma_f32 v[86:87], v[86:87], s[74:75], v[154:155] op_sel_hi:[1,0,1]
	v_pk_fma_f32 v[92:93], v[92:93], s[74:75], v[154:155] op_sel_hi:[1,0,1]
	v_pk_mul_f32 v[86:87], v[208:209], v[86:87]
	v_pk_mul_f32 v[92:93], v[210:211], v[92:93]
	v_exp_f32_e32 v86, v86
	v_exp_f32_e32 v87, v87
	v_exp_f32_e32 v92, v92
	v_exp_f32_e32 v93, v93
	v_pk_mul_f32 v[208:209], v[208:209], v[144:145]
	v_pk_mul_f32 v[210:211], v[210:211], v[146:147]
	v_pk_add_f32 v[86:87], v[86:87], v[152:153]
	v_pk_add_f32 v[92:93], v[92:93], v[152:153]
	v_rcp_f32_e32 v86, v86
	v_rcp_f32_e32 v87, v87
	v_rcp_f32_e32 v92, v92
	v_rcp_f32_e32 v93, v93
	s_nop 0
	v_pk_mul_f32 v[208:209], v[208:209], v[86:87]
	v_pk_mul_f32 v[210:211], v[210:211], v[92:93]
	v_cvt_pk_bf16_f32 v144, v208, v209
	v_cvt_pk_bf16_f32 v145, v210, v211
	v_pk_fma_f32 v[208:209], v[62:63], v[204:205], v[230:231]
	v_pk_fma_f32 v[210:211], v[64:65], v[206:207], v[232:233]
	v_fmac_f32_dpp v208, v62, v246 row_shr:1 row_mask:0xf bank_mask:0xf
	v_fmac_f32_dpp v209, v63, v247 row_shr:1 row_mask:0xf bank_mask:0xf
	v_fmac_f32_dpp v210, v64, v248 row_shr:1 row_mask:0xf bank_mask:0xf
	v_fmac_f32_dpp v211, v65, v249 row_shr:1 row_mask:0xf bank_mask:0xf
	v_fmac_f32_dpp v208, v62, v238 row_shr:2 row_mask:0xf bank_mask:0xf
	v_fmac_f32_dpp v209, v63, v239 row_shr:2 row_mask:0xf bank_mask:0xf
	v_fmac_f32_dpp v210, v64, v240 row_shr:2 row_mask:0xf bank_mask:0xf
	v_fmac_f32_dpp v211, v65, v241 row_shr:2 row_mask:0xf bank_mask:0xf
	v_fmac_f32_e32 v208, v108, v200
	v_fmac_f32_e32 v209, v109, v200
	v_fmac_f32_e32 v210, v110, v200
	v_fmac_f32_e32 v211, v111, v200
	v_pk_mul_f32 v[86:87], v[208:209], v[208:209]
	v_pk_mul_f32 v[92:93], v[210:211], v[210:211]
	v_pk_fma_f32 v[86:87], v[86:87], s[74:75], v[154:155] op_sel_hi:[1,0,1]
	v_pk_fma_f32 v[92:93], v[92:93], s[74:75], v[154:155] op_sel_hi:[1,0,1]
	v_pk_mul_f32 v[86:87], v[208:209], v[86:87]
	v_pk_mul_f32 v[92:93], v[210:211], v[92:93]
	v_exp_f32_e32 v86, v86
	v_exp_f32_e32 v87, v87
	v_exp_f32_e32 v92, v92
	v_exp_f32_e32 v93, v93
	v_pk_mul_f32 v[208:209], v[208:209], v[58:59]
	v_pk_mul_f32 v[210:211], v[210:211], v[60:61]
	v_pk_add_f32 v[86:87], v[86:87], v[152:153]
	v_pk_add_f32 v[92:93], v[92:93], v[152:153]
	v_rcp_f32_e32 v86, v86
	v_rcp_f32_e32 v87, v87
	v_rcp_f32_e32 v92, v92
	v_rcp_f32_e32 v93, v93
	s_nop 0
	v_pk_mul_f32 v[208:209], v[208:209], v[86:87]
	v_pk_mul_f32 v[210:211], v[210:211], v[92:93]
	v_cvt_pk_bf16_f32 v146, v208, v209
	v_cvt_pk_bf16_f32 v147, v210, v211
	s_mov_b64 exec, s[84:85]
	global_store_dwordx4 v98, v[148:151], s[42:43]
	global_store_dwordx4 v98, v[62:65], s[42:43] offset:16
	s_mov_b64 exec, -1
	global_store_dwordx4 v212, v[144:147], s[80:81]
	s_add_u32 s42, s42, 0xb000
	s_addc_u32 s43, s43, 0
	s_add_u32 s80, s80, 0x16000
	s_addc_u32 s81, s81, 0
	v_pk_fma_f32 v[208:209], v[140:141], v[250:251], v[226:227]
	v_pk_fma_f32 v[210:211], v[142:143], v[252:253], v[228:229]
	v_fmac_f32_dpp v208, v140, v242 row_shr:1 row_mask:0xf bank_mask:0xf
	v_fmac_f32_dpp v209, v141, v243 row_shr:1 row_mask:0xf bank_mask:0xf
	v_fmac_f32_dpp v210, v142, v244 row_shr:1 row_mask:0xf bank_mask:0xf
	v_fmac_f32_dpp v211, v143, v245 row_shr:1 row_mask:0xf bank_mask:0xf
	v_fmac_f32_dpp v208, v140, v234 row_shr:2 row_mask:0xf bank_mask:0xf
	v_fmac_f32_dpp v209, v141, v235 row_shr:2 row_mask:0xf bank_mask:0xf
	v_fmac_f32_dpp v210, v142, v236 row_shr:2 row_mask:0xf bank_mask:0xf
	v_fmac_f32_dpp v211, v143, v237 row_shr:2 row_mask:0xf bank_mask:0xf
	v_fmac_f32_dpp v208, v104, v200 row_shl:2 row_mask:0xf bank_mask:0xf
	v_fmac_f32_dpp v209, v105, v200 row_shl:2 row_mask:0xf bank_mask:0xf
	v_fmac_f32_dpp v210, v106, v200 row_shl:2 row_mask:0xf bank_mask:0xf
	v_fmac_f32_dpp v211, v107, v200 row_shl:2 row_mask:0xf bank_mask:0xf
	v_pk_mul_f32 v[86:87], v[208:209], v[208:209]
	v_pk_mul_f32 v[92:93], v[210:211], v[210:211]
	v_pk_fma_f32 v[86:87], v[86:87], s[74:75], v[154:155] op_sel_hi:[1,0,1]
	v_pk_fma_f32 v[92:93], v[92:93], s[74:75], v[154:155] op_sel_hi:[1,0,1]
	v_pk_mul_f32 v[86:87], v[208:209], v[86:87]
	v_pk_mul_f32 v[92:93], v[210:211], v[92:93]
	v_exp_f32_e32 v86, v86
	v_exp_f32_e32 v87, v87
;     __device__ __forceinline__ void operator()(const f32x4 (&acc)[2][2][4][2], const Unit& u, int wr, int wc, int fr, int fq) const {
;     ...
;                     const int r = row0 + ai * HALF + m * 16; const float rs = rstd[ai][m];
;                     const f32x4 a = acc[ai][0][m][n] * rs, b = acc[ai][1][m][n] * rs; f32x4 p1, p2;
;                     if (!smp) {
; #pragma unroll
;                         for (int e2 = 0; e2 < 4; ++e2) { const float s1 = fr == 15 ? pa[e2] : a[e2], s2 = fr >= 14 ? pa[e2] : a[e2]; p1[e2] = ror1(s1); p2[e2] = ror2(s2); }
;                         if (ai == 0 && wr == 0 && m == 0 && fr < 2) { *(f32x4*)(EA + ((size_t)u.pm * 4 + fr) * FF + j0 + 4 * n) = a; *(f32x4*)(EB + ((size_t)u.pm * 2 + fr) * FF + j0 + 4 * n) = b; }
;                         if (ai == 1 && wr == 1 && m == 3 && fr >= 14) { *(f32x4*)(EA + ((size_t)u.pm * 4 + 2 + (fr - 14)) * FF + j0 + 4 * n) = a;
;                             if ((u.pm & 7) == 7) *(f32x4*)(o_conv_p + ((size_t)(u.pm >> 3) * 2 + (fr - 14)) * FF + j0 + 4 * n) = a; }
;                     } else {
;                         const int t = fr & 7, bb = (r - 16384) >> 3;
; #pragma unroll
;                         for (int e2 = 0; e2 < 4; ++e2) { p1[e2] = ror1(a[e2]); p2[e2] = ror2(a[e2]); }
;                         if (t < 2) { const f32x4 h1 = *(const f32x4*)(state_conv + ((size_t)bb * 2 + 1) * FF + j0 + 4 * n);
;                             if (t == 0) { p1 = h1; p2 = *(const f32x4*)(state_conv + ((size_t)bb * 2) * FF + j0 + 4 * n); } else p2 = h1; }
;                         if (t >= 6) *(f32x4*)(o_conv_s + ((size_t)bb * 2 + (t - 6)) * FF + j0 + 4 * n) = a;
;                     }
;                     f32x4 hv;
; #pragma unroll
;                     for (int e2 = 0; e2 < 1; ++e2) {
;                         const f32x4 c4 = cb + w0 * p2 + w1 * p1 + w2 * a;
;                         const f32x4 z = c4 * ((c4 * c4) * (-0.10294324f) + (-2.3022082f));
;                         f32x4 den; den[0] = 1.f + __builtin_amdgcn_exp2f(z[0]); den[1] = 1.f + __builtin_amdgcn_exp2f(z[1]); den[2] = 1.f + __builtin_amdgcn_exp2f(z[2]); den[3] = 1.f + __builtin_amdgcn_exp2f(z[3]);
;                         f32x4 rc; rc[0] = frcp(den[0]); rc[1] = frcp(den[1]); rc[2] = frcp(den[2]); rc[3] = frcp(den[3]);
;                         hv = (c4 * rc) * b; }
	v_exp_f32_e32 v92, v92
	v_exp_f32_e32 v93, v93
	v_pk_mul_f32 v[208:209], v[208:209], v[136:137]
	v_pk_mul_f32 v[210:211], v[210:211], v[138:139]
	v_pk_add_f32 v[86:87], v[86:87], v[152:153]
	v_pk_add_f32 v[92:93], v[92:93], v[152:153]
	v_rcp_f32_e32 v86, v86
	v_rcp_f32_e32 v87, v87
	v_rcp_f32_e32 v92, v92
	v_rcp_f32_e32 v93, v93
	s_nop 0
	v_pk_mul_f32 v[208:209], v[208:209], v[86:87]
	v_pk_mul_f32 v[210:211], v[210:211], v[92:93]
	v_cvt_pk_bf16_f32 v136, v208, v209
	v_cvt_pk_bf16_f32 v137, v210, v211
	v_pk_fma_f32 v[208:209], v[54:55], v[204:205], v[230:231]
	v_pk_fma_f32 v[210:211], v[56:57], v[206:207], v[232:233]
	v_fmac_f32_dpp v208, v54, v246 row_shr:1 row_mask:0xf bank_mask:0xf
	v_fmac_f32_dpp v209, v55, v247 row_shr:1 row_mask:0xf bank_mask:0xf
	v_fmac_f32_dpp v210, v56, v248 row_shr:1 row_mask:0xf bank_mask:0xf
	v_fmac_f32_dpp v211, v57, v249 row_shr:1 row_mask:0xf bank_mask:0xf
	v_fmac_f32_dpp v208, v54, v238 row_shr:2 row_mask:0xf bank_mask:0xf
	v_fmac_f32_dpp v209, v55, v239 row_shr:2 row_mask:0xf bank_mask:0xf
	v_fmac_f32_dpp v210, v56, v240 row_shr:2 row_mask:0xf bank_mask:0xf
	v_fmac_f32_dpp v211, v57, v241 row_shr:2 row_mask:0xf bank_mask:0xf
	v_fmac_f32_dpp v208, v108, v200 row_shl:2 row_mask:0xf bank_mask:0xf
	v_fmac_f32_dpp v209, v109, v200 row_shl:2 row_mask:0xf bank_mask:0xf
	v_fmac_f32_dpp v210, v110, v200 row_shl:2 row_mask:0xf bank_mask:0xf
	v_fmac_f32_dpp v211, v111, v200 row_shl:2 row_mask:0xf bank_mask:0xf
	v_pk_mul_f32 v[86:87], v[208:209], v[208:209]
	v_pk_mul_f32 v[92:93], v[210:211], v[210:211]
	v_pk_fma_f32 v[86:87], v[86:87], s[74:75], v[154:155] op_sel_hi:[1,0,1]
	v_pk_fma_f32 v[92:93], v[92:93], s[74:75], v[154:155] op_sel_hi:[1,0,1]
	v_pk_mul_f32 v[86:87], v[208:209], v[86:87]
	v_pk_mul_f32 v[92:93], v[210:211], v[92:93]
	v_exp_f32_e32 v86, v86
	v_exp_f32_e32 v87, v87
	v_exp_f32_e32 v92, v92
	v_exp_f32_e32 v93, v93
	v_pk_mul_f32 v[208:209], v[208:209], v[50:51]
	v_pk_mul_f32 v[210:211], v[210:211], v[52:53]
	v_pk_add_f32 v[86:87], v[86:87], v[152:153]
	v_pk_add_f32 v[92:93], v[92:93], v[152:153]
	v_rcp_f32_e32 v86, v86
	v_rcp_f32_e32 v87, v87
	v_rcp_f32_e32 v92, v92
	v_rcp_f32_e32 v93, v93
	s_nop 0
	v_pk_mul_f32 v[208:209], v[208:209], v[86:87]
	v_pk_mul_f32 v[210:211], v[210:211], v[92:93]
	v_cvt_pk_bf16_f32 v138, v208, v209
	v_cvt_pk_bf16_f32 v139, v210, v211
	s_mov_b64 exec, s[84:85]
	global_store_dwordx4 v98, v[140:143], s[42:43]
	global_store_dwordx4 v98, v[54:57], s[42:43] offset:16
	s_mov_b64 exec, -1
	global_store_dwordx4 v212, v[136:139], s[80:81]
	s_add_u32 s42, s42, 0xb000
	s_addc_u32 s43, s43, 0
	s_add_u32 s80, s80, 0x16000
	s_addc_u32 s81, s81, 0
	v_pk_fma_f32 v[208:209], v[132:133], v[250:251], v[226:227]
	v_pk_fma_f32 v[210:211], v[134:135], v[252:253], v[228:229]
	v_fmac_f32_dpp v208, v132, v242 row_shr:1 row_mask:0xf bank_mask:0xf
	v_fmac_f32_dpp v209, v133, v243 row_shr:1 row_mask:0xf bank_mask:0xf
	v_fmac_f32_dpp v210, v134, v244 row_shr:1 row_mask:0xf bank_mask:0xf
	v_fmac_f32_dpp v211, v135, v245 row_shr:1 row_mask:0xf bank_mask:0xf
	v_fmac_f32_dpp v208, v132, v234 row_shr:2 row_mask:0xf bank_mask:0xf
	v_fmac_f32_dpp v209, v133, v235 row_shr:2 row_mask:0xf bank_mask:0xf
	v_fmac_f32_dpp v210, v134, v236 row_shr:2 row_mask:0xf bank_mask:0xf
	v_fmac_f32_dpp v211, v135, v237 row_shr:2 row_mask:0xf bank_mask:0xf
	v_fmac_f32_dpp v208, v104, v200 row_shl:4 row_mask:0xf bank_mask:0xf
	v_fmac_f32_dpp v209, v105, v200 row_shl:4 row_mask:0xf bank_mask:0xf
	v_fmac_f32_dpp v210, v106, v200 row_shl:4 row_mask:0xf bank_mask:0xf
	v_fmac_f32_dpp v211, v107, v200 row_shl:4 row_mask:0xf bank_mask:0xf
	v_pk_mul_f32 v[86:87], v[208:209], v[208:209]
	v_pk_mul_f32 v[92:93], v[210:211], v[210:211]
	v_pk_fma_f32 v[86:87], v[86:87], s[74:75], v[154:155] op_sel_hi:[1,0,1]
	v_pk_fma_f32 v[92:93], v[92:93], s[74:75], v[154:155] op_sel_hi:[1,0,1]
	v_pk_mul_f32 v[86:87], v[208:209], v[86:87]
	v_pk_mul_f32 v[92:93], v[210:211], v[92:93]
	v_exp_f32_e32 v86, v86
	v_exp_f32_e32 v87, v87
	v_exp_f32_e32 v92, v92
	v_exp_f32_e32 v93, v93
	v_pk_mul_f32 v[208:209], v[208:209], v[128:129]
	v_pk_mul_f32 v[210:211], v[210:211], v[130:131]
	v_pk_add_f32 v[86:87], v[86:87], v[152:153]
	v_pk_add_f32 v[92:93], v[92:93], v[152:153]
	v_rcp_f32_e32 v86, v86
	v_rcp_f32_e32 v87, v87
	v_rcp_f32_e32 v92, v92
	v_rcp_f32_e32 v93, v93
	s_nop 0
	v_pk_mul_f32 v[208:209], v[208:209], v[86:87]
	v_pk_mul_f32 v[210:211], v[210:211], v[92:93]
	v_cvt_pk_bf16_f32 v128, v208, v209
	v_cvt_pk_bf16_f32 v129, v210, v211
	v_pk_fma_f32 v[208:209], v[46:47], v[204:205], v[230:231]
	v_pk_fma_f32 v[210:211], v[48:49], v[206:207], v[232:233]
	v_fmac_f32_dpp v208, v46, v246 row_shr:1 row_mask:0xf bank_mask:0xf
	v_fmac_f32_dpp v209, v47, v247 row_shr:1 row_mask:0xf bank_mask:0xf
	v_fmac_f32_dpp v210, v48, v248 row_shr:1 row_mask:0xf bank_mask:0xf
	v_fmac_f32_dpp v211, v49, v249 row_shr:1 row_mask:0xf bank_mask:0xf
	v_fmac_f32_dpp v208, v46, v238 row_shr:2 row_mask:0xf bank_mask:0xf
	v_fmac_f32_dpp v209, v47, v239 row_shr:2 row_mask:0xf bank_mask:0xf
	v_fmac_f32_dpp v210, v48, v240 row_shr:2 row_mask:0xf bank_mask:0xf
	v_fmac_f32_dpp v211, v49, v241 row_shr:2 row_mask:0xf bank_mask:0xf
	v_fmac_f32_dpp v208, v108, v200 row_shl:4 row_mask:0xf bank_mask:0xf
	v_fmac_f32_dpp v209, v109, v200 row_shl:4 row_mask:0xf bank_mask:0xf
	v_fmac_f32_dpp v210, v110, v200 row_shl:4 row_mask:0xf bank_mask:0xf
	v_fmac_f32_dpp v211, v111, v200 row_shl:4 row_mask:0xf bank_mask:0xf
	v_pk_mul_f32 v[86:87], v[208:209], v[208:209]
	v_pk_mul_f32 v[92:93], v[210:211], v[210:211]
	v_pk_fma_f32 v[86:87], v[86:87], s[74:75], v[154:155] op_sel_hi:[1,0,1]
;     __device__ __forceinline__ void operator()(const f32x4 (&acc)[2][2][4][2], const Unit& u, int wr, int wc, int fr, int fq) const {
;     ...
;                     const int r = row0 + ai * HALF + m * 16; const float rs = rstd[ai][m];
;                     const f32x4 a = acc[ai][0][m][n] * rs, b = acc[ai][1][m][n] * rs; f32x4 p1, p2;
;                     if (!smp) {
; #pragma unroll
;                         for (int e2 = 0; e2 < 4; ++e2) { const float s1 = fr == 15 ? pa[e2] : a[e2], s2 = fr >= 14 ? pa[e2] : a[e2]; p1[e2] = ror1(s1); p2[e2] = ror2(s2); }
;                         if (ai == 0 && wr == 0 && m == 0 && fr < 2) { *(f32x4*)(EA + ((size_t)u.pm * 4 + fr) * FF + j0 + 4 * n) = a; *(f32x4*)(EB + ((size_t)u.pm * 2 + fr) * FF + j0 + 4 * n) = b; }
;                         if (ai == 1 && wr == 1 && m == 3 && fr >= 14) { *(f32x4*)(EA + ((size_t)u.pm * 4 + 2 + (fr - 14)) * FF + j0 + 4 * n) = a;
;                             if ((u.pm & 7) == 7) *(f32x4*)(o_conv_p + ((size_t)(u.pm >> 3) * 2 + (fr - 14)) * FF + j0 + 4 * n) = a; }
;                     } else {
;                         const int t = fr & 7, bb = (r - 16384) >> 3;
; #pragma unroll
;                         for (int e2 = 0; e2 < 4; ++e2) { p1[e2] = ror1(a[e2]); p2[e2] = ror2(a[e2]); }
;                         if (t < 2) { const f32x4 h1 = *(const f32x4*)(state_conv + ((size_t)bb * 2 + 1) * FF + j0 + 4 * n);
;                             if (t == 0) { p1 = h1; p2 = *(const f32x4*)(state_conv + ((size_t)bb * 2) * FF + j0 + 4 * n); } else p2 = h1; }
;                         if (t >= 6) *(f32x4*)(o_conv_s + ((size_t)bb * 2 + (t - 6)) * FF + j0 + 4 * n) = a;
;                     }
;                     f32x4 hv;
; #pragma unroll
;                     for (int e2 = 0; e2 < 1; ++e2) {
;                         const f32x4 c4 = cb + w0 * p2 + w1 * p1 + w2 * a;
;                         const f32x4 z = c4 * ((c4 * c4) * (-0.10294324f) + (-2.3022082f));
;                         f32x4 den; den[0] = 1.f + __builtin_amdgcn_exp2f(z[0]); den[1] = 1.f + __builtin_amdgcn_exp2f(z[1]); den[2] = 1.f + __builtin_amdgcn_exp2f(z[2]); den[3] = 1.f + __builtin_amdgcn_exp2f(z[3]);
;                         f32x4 rc; rc[0] = frcp(den[0]); rc[1] = frcp(den[1]); rc[2] = frcp(den[2]); rc[3] = frcp(den[3]);
;                         hv = (c4 * rc) * b; }
	v_pk_fma_f32 v[92:93], v[92:93], s[74:75], v[154:155] op_sel_hi:[1,0,1]
	v_pk_mul_f32 v[86:87], v[208:209], v[86:87]
	v_pk_mul_f32 v[92:93], v[210:211], v[92:93]
	v_exp_f32_e32 v86, v86
	v_exp_f32_e32 v87, v87
	v_exp_f32_e32 v92, v92
	v_exp_f32_e32 v93, v93
	v_pk_mul_f32 v[208:209], v[208:209], v[42:43]
	v_pk_mul_f32 v[210:211], v[210:211], v[44:45]
	v_pk_add_f32 v[86:87], v[86:87], v[152:153]
	v_pk_add_f32 v[92:93], v[92:93], v[152:153]
	v_rcp_f32_e32 v86, v86
	v_rcp_f32_e32 v87, v87
	v_rcp_f32_e32 v92, v92
	v_rcp_f32_e32 v93, v93
	s_nop 0
	v_pk_mul_f32 v[208:209], v[208:209], v[86:87]
	v_pk_mul_f32 v[210:211], v[210:211], v[92:93]
	v_cvt_pk_bf16_f32 v130, v208, v209
	v_cvt_pk_bf16_f32 v131, v210, v211
	s_mov_b64 exec, s[84:85]
	global_store_dwordx4 v98, v[132:135], s[42:43]
	global_store_dwordx4 v98, v[46:49], s[42:43] offset:16
	s_mov_b64 exec, -1
	global_store_dwordx4 v212, v[128:131], s[80:81]
	s_add_u32 s42, s42, 0xb000
	s_addc_u32 s43, s43, 0
	s_add_u32 s80, s80, 0x16000
	s_addc_u32 s81, s81, 0
	v_pk_fma_f32 v[208:209], v[124:125], v[250:251], v[226:227]
	v_pk_fma_f32 v[210:211], v[126:127], v[252:253], v[228:229]
	v_fmac_f32_dpp v208, v124, v242 row_shr:1 row_mask:0xf bank_mask:0xf
	v_fmac_f32_dpp v209, v125, v243 row_shr:1 row_mask:0xf bank_mask:0xf
	v_fmac_f32_dpp v210, v126, v244 row_shr:1 row_mask:0xf bank_mask:0xf
	v_fmac_f32_dpp v211, v127, v245 row_shr:1 row_mask:0xf bank_mask:0xf
	v_fmac_f32_dpp v208, v124, v234 row_shr:2 row_mask:0xf bank_mask:0xf
	v_fmac_f32_dpp v209, v125, v235 row_shr:2 row_mask:0xf bank_mask:0xf
	v_fmac_f32_dpp v210, v126, v236 row_shr:2 row_mask:0xf bank_mask:0xf
	v_fmac_f32_dpp v211, v127, v237 row_shr:2 row_mask:0xf bank_mask:0xf
	v_fmac_f32_dpp v208, v104, v200 row_shl:6 row_mask:0xf bank_mask:0xf
	v_fmac_f32_dpp v209, v105, v200 row_shl:6 row_mask:0xf bank_mask:0xf
	v_fmac_f32_dpp v210, v106, v200 row_shl:6 row_mask:0xf bank_mask:0xf
	v_fmac_f32_dpp v211, v107, v200 row_shl:6 row_mask:0xf bank_mask:0xf
	v_pk_mul_f32 v[86:87], v[208:209], v[208:209]
	v_pk_mul_f32 v[92:93], v[210:211], v[210:211]
	v_pk_fma_f32 v[86:87], v[86:87], s[74:75], v[154:155] op_sel_hi:[1,0,1]
	v_pk_fma_f32 v[92:93], v[92:93], s[74:75], v[154:155] op_sel_hi:[1,0,1]
	v_pk_mul_f32 v[86:87], v[208:209], v[86:87]
	v_pk_mul_f32 v[92:93], v[210:211], v[92:93]
	v_exp_f32_e32 v86, v86
	v_exp_f32_e32 v87, v87
	v_exp_f32_e32 v92, v92
	v_exp_f32_e32 v93, v93
	v_pk_mul_f32 v[208:209], v[208:209], v[94:95]
	v_pk_mul_f32 v[210:211], v[210:211], v[96:97]
	v_pk_add_f32 v[86:87], v[86:87], v[152:153]
	v_pk_add_f32 v[92:93], v[92:93], v[152:153]
	v_rcp_f32_e32 v86, v86
	v_rcp_f32_e32 v87, v87
	v_rcp_f32_e32 v92, v92
	v_rcp_f32_e32 v93, v93
	s_nop 0
	v_pk_mul_f32 v[208:209], v[208:209], v[86:87]
	v_pk_mul_f32 v[210:211], v[210:211], v[92:93]
	v_cvt_pk_bf16_f32 v94, v208, v209
	v_cvt_pk_bf16_f32 v95, v210, v211
	v_pk_fma_f32 v[208:209], v[38:39], v[204:205], v[230:231]
	v_pk_fma_f32 v[210:211], v[40:41], v[206:207], v[232:233]
	v_fmac_f32_dpp v208, v38, v246 row_shr:1 row_mask:0xf bank_mask:0xf
	v_fmac_f32_dpp v209, v39, v247 row_shr:1 row_mask:0xf bank_mask:0xf
	v_fmac_f32_dpp v210, v40, v248 row_shr:1 row_mask:0xf bank_mask:0xf
	v_fmac_f32_dpp v211, v41, v249 row_shr:1 row_mask:0xf bank_mask:0xf
	v_fmac_f32_dpp v208, v38, v238 row_shr:2 row_mask:0xf bank_mask:0xf
	v_fmac_f32_dpp v209, v39, v239 row_shr:2 row_mask:0xf bank_mask:0xf
	v_fmac_f32_dpp v210, v40, v240 row_shr:2 row_mask:0xf bank_mask:0xf
	v_fmac_f32_dpp v211, v41, v241 row_shr:2 row_mask:0xf bank_mask:0xf
	v_fmac_f32_dpp v208, v108, v200 row_shl:6 row_mask:0xf bank_mask:0xf
	v_fmac_f32_dpp v209, v109, v200 row_shl:6 row_mask:0xf bank_mask:0xf
	v_fmac_f32_dpp v210, v110, v200 row_shl:6 row_mask:0xf bank_mask:0xf
	v_fmac_f32_dpp v211, v111, v200 row_shl:6 row_mask:0xf bank_mask:0xf
	v_pk_mul_f32 v[86:87], v[208:209], v[208:209]
	v_pk_mul_f32 v[92:93], v[210:211], v[210:211]
	v_pk_fma_f32 v[86:87], v[86:87], s[74:75], v[154:155] op_sel_hi:[1,0,1]
	v_pk_fma_f32 v[92:93], v[92:93], s[74:75], v[154:155] op_sel_hi:[1,0,1]
	v_pk_mul_f32 v[86:87], v[208:209], v[86:87]
	v_pk_mul_f32 v[92:93], v[210:211], v[92:93]
	v_exp_f32_e32 v86, v86
	v_exp_f32_e32 v87, v87
	v_exp_f32_e32 v92, v92
	v_exp_f32_e32 v93, v93
	v_pk_mul_f32 v[208:209], v[208:209], v[34:35]
	v_pk_mul_f32 v[210:211], v[210:211], v[36:37]
	v_pk_add_f32 v[86:87], v[86:87], v[152:153]
	v_pk_add_f32 v[92:93], v[92:93], v[152:153]
	v_rcp_f32_e32 v86, v86
	v_rcp_f32_e32 v87, v87
	v_rcp_f32_e32 v92, v92
	v_rcp_f32_e32 v93, v93
	s_nop 0
	v_pk_mul_f32 v[208:209], v[208:209], v[86:87]
	v_pk_mul_f32 v[210:211], v[210:211], v[92:93]
	v_cvt_pk_bf16_f32 v96, v208, v209
	v_cvt_pk_bf16_f32 v97, v210, v211
	s_mov_b64 exec, s[84:85]
	global_store_dwordx4 v98, v[124:127], s[42:43]
	global_store_dwordx4 v98, v[38:41], s[42:43] offset:16
	s_mov_b64 exec, -1
	global_store_dwordx4 v212, v[94:97], s[80:81]
	s_add_u32 s42, s42, 0x37000
	s_addc_u32 s43, s43, 0
	s_add_u32 s80, s80, 0x6e000
	s_addc_u32 s81, s81, 0
	v_pk_fma_f32 v[208:209], v[120:121], v[250:251], v[226:227]
	v_pk_fma_f32 v[210:211], v[122:123], v[252:253], v[228:229]
	v_fmac_f32_dpp v208, v120, v242 row_shr:1 row_mask:0xf bank_mask:0xf
	v_fmac_f32_dpp v209, v121, v243 row_shr:1 row_mask:0xf bank_mask:0xf
	v_fmac_f32_dpp v210, v122, v244 row_shr:1 row_mask:0xf bank_mask:0xf
	v_fmac_f32_dpp v211, v123, v245 row_shr:1 row_mask:0xf bank_mask:0xf
	v_fmac_f32_dpp v208, v120, v234 row_shr:2 row_mask:0xf bank_mask:0xf
	v_fmac_f32_dpp v209, v121, v235 row_shr:2 row_mask:0xf bank_mask:0xf
	v_fmac_f32_dpp v210, v122, v236 row_shr:2 row_mask:0xf bank_mask:0xf
	v_fmac_f32_dpp v211, v123, v237 row_shr:2 row_mask:0xf bank_mask:0xf
;     __device__ __forceinline__ void operator()(const f32x4 (&acc)[2][2][4][2], const Unit& u, int wr, int wc, int fr, int fq) const {
;     ...
;                     const int r = row0 + ai * HALF + m * 16; const float rs = rstd[ai][m];
;                     const f32x4 a = acc[ai][0][m][n] * rs, b = acc[ai][1][m][n] * rs; f32x4 p1, p2;
;                     if (!smp) {
; #pragma unroll
;                         for (int e2 = 0; e2 < 4; ++e2) { const float s1 = fr == 15 ? pa[e2] : a[e2], s2 = fr >= 14 ? pa[e2] : a[e2]; p1[e2] = ror1(s1); p2[e2] = ror2(s2); }
;                         if (ai == 0 && wr == 0 && m == 0 && fr < 2) { *(f32x4*)(EA + ((size_t)u.pm * 4 + fr) * FF + j0 + 4 * n) = a; *(f32x4*)(EB + ((size_t)u.pm * 2 + fr) * FF + j0 + 4 * n) = b; }
;                         if (ai == 1 && wr == 1 && m == 3 && fr >= 14) { *(f32x4*)(EA + ((size_t)u.pm * 4 + 2 + (fr - 14)) * FF + j0 + 4 * n) = a;
;                             if ((u.pm & 7) == 7) *(f32x4*)(o_conv_p + ((size_t)(u.pm >> 3) * 2 + (fr - 14)) * FF + j0 + 4 * n) = a; }
;                     } else {
;                         const int t = fr & 7, bb = (r - 16384) >> 3;
; #pragma unroll
;                         for (int e2 = 0; e2 < 4; ++e2) { p1[e2] = ror1(a[e2]); p2[e2] = ror2(a[e2]); }
;                         if (t < 2) { const f32x4 h1 = *(const f32x4*)(state_conv + ((size_t)bb * 2 + 1) * FF + j0 + 4 * n);
;                             if (t == 0) { p1 = h1; p2 = *(const f32x4*)(state_conv + ((size_t)bb * 2) * FF + j0 + 4 * n); } else p2 = h1; }
;                         if (t >= 6) *(f32x4*)(o_conv_s + ((size_t)bb * 2 + (t - 6)) * FF + j0 + 4 * n) = a;
;                     }
;                     f32x4 hv;
; #pragma unroll
;                     for (int e2 = 0; e2 < 1; ++e2) {
;                         const f32x4 c4 = cb + w0 * p2 + w1 * p1 + w2 * a;
;                         const f32x4 z = c4 * ((c4 * c4) * (-0.10294324f) + (-2.3022082f));
;                         f32x4 den; den[0] = 1.f + __builtin_amdgcn_exp2f(z[0]); den[1] = 1.f + __builtin_amdgcn_exp2f(z[1]); den[2] = 1.f + __builtin_amdgcn_exp2f(z[2]); den[3] = 1.f + __builtin_amdgcn_exp2f(z[3]);
;                         f32x4 rc; rc[0] = frcp(den[0]); rc[1] = frcp(den[1]); rc[2] = frcp(den[2]); rc[3] = frcp(den[3]);
;                         hv = (c4 * rc) * b; }
	v_fmac_f32_e32 v208, v112, v200
	v_fmac_f32_e32 v209, v113, v200
	v_fmac_f32_e32 v210, v114, v200
	v_fmac_f32_e32 v211, v115, v200
	v_pk_mul_f32 v[86:87], v[208:209], v[208:209]
	v_pk_mul_f32 v[92:93], v[210:211], v[210:211]
	v_pk_fma_f32 v[86:87], v[86:87], s[74:75], v[154:155] op_sel_hi:[1,0,1]
	v_pk_fma_f32 v[92:93], v[92:93], s[74:75], v[154:155] op_sel_hi:[1,0,1]
	v_pk_mul_f32 v[86:87], v[208:209], v[86:87]
	v_pk_mul_f32 v[92:93], v[210:211], v[92:93]
	v_exp_f32_e32 v86, v86
	v_exp_f32_e32 v87, v87
	v_exp_f32_e32 v92, v92
	v_exp_f32_e32 v93, v93
	v_pk_mul_f32 v[208:209], v[208:209], v[100:101]
	v_pk_mul_f32 v[210:211], v[210:211], v[102:103]
	v_pk_add_f32 v[86:87], v[86:87], v[152:153]
	v_pk_add_f32 v[92:93], v[92:93], v[152:153]
	v_rcp_f32_e32 v86, v86
	v_rcp_f32_e32 v87, v87
	v_rcp_f32_e32 v92, v92
	v_rcp_f32_e32 v93, v93
	s_nop 0
	v_pk_mul_f32 v[208:209], v[208:209], v[86:87]
	v_pk_mul_f32 v[210:211], v[210:211], v[92:93]
	v_cvt_pk_bf16_f32 v100, v208, v209
	v_cvt_pk_bf16_f32 v101, v210, v211
	v_pk_fma_f32 v[208:209], v[30:31], v[204:205], v[230:231]
	v_pk_fma_f32 v[210:211], v[32:33], v[206:207], v[232:233]
	v_fmac_f32_dpp v208, v30, v246 row_shr:1 row_mask:0xf bank_mask:0xf
	v_fmac_f32_dpp v209, v31, v247 row_shr:1 row_mask:0xf bank_mask:0xf
	v_fmac_f32_dpp v210, v32, v248 row_shr:1 row_mask:0xf bank_mask:0xf
	v_fmac_f32_dpp v211, v33, v249 row_shr:1 row_mask:0xf bank_mask:0xf
	v_fmac_f32_dpp v208, v30, v238 row_shr:2 row_mask:0xf bank_mask:0xf
	v_fmac_f32_dpp v209, v31, v239 row_shr:2 row_mask:0xf bank_mask:0xf
	v_fmac_f32_dpp v210, v32, v240 row_shr:2 row_mask:0xf bank_mask:0xf
	v_fmac_f32_dpp v211, v33, v241 row_shr:2 row_mask:0xf bank_mask:0xf
	v_fmac_f32_e32 v208, v116, v200
	v_fmac_f32_e32 v209, v117, v200
	v_fmac_f32_e32 v210, v118, v200
	v_fmac_f32_e32 v211, v119, v200
	v_pk_mul_f32 v[86:87], v[208:209], v[208:209]
	v_pk_mul_f32 v[92:93], v[210:211], v[210:211]
	v_pk_fma_f32 v[86:87], v[86:87], s[74:75], v[154:155] op_sel_hi:[1,0,1]
	v_pk_fma_f32 v[92:93], v[92:93], s[74:75], v[154:155] op_sel_hi:[1,0,1]
	v_pk_mul_f32 v[86:87], v[208:209], v[86:87]
	v_pk_mul_f32 v[92:93], v[210:211], v[92:93]
	v_exp_f32_e32 v86, v86
	v_exp_f32_e32 v87, v87
	v_exp_f32_e32 v92, v92
	v_exp_f32_e32 v93, v93
	v_pk_mul_f32 v[208:209], v[208:209], v[26:27]
	v_pk_mul_f32 v[210:211], v[210:211], v[28:29]
	v_pk_add_f32 v[86:87], v[86:87], v[152:153]
	v_pk_add_f32 v[92:93], v[92:93], v[152:153]
	v_rcp_f32_e32 v86, v86
	v_rcp_f32_e32 v87, v87
	v_rcp_f32_e32 v92, v92
	v_rcp_f32_e32 v93, v93
	s_nop 0
	v_pk_mul_f32 v[208:209], v[208:209], v[86:87]
	v_pk_mul_f32 v[210:211], v[210:211], v[92:93]
	v_cvt_pk_bf16_f32 v102, v208, v209
	v_cvt_pk_bf16_f32 v103, v210, v211
	s_mov_b64 exec, s[84:85]
	global_store_dwordx4 v98, v[120:123], s[42:43]
	global_store_dwordx4 v98, v[30:33], s[42:43] offset:16
	s_mov_b64 exec, -1
	global_store_dwordx4 v212, v[100:103], s[80:81]
	s_add_u32 s42, s42, 0xb000
	s_addc_u32 s43, s43, 0
	s_add_u32 s80, s80, 0x16000
	s_addc_u32 s81, s81, 0
	v_pk_fma_f32 v[208:209], v[88:89], v[250:251], v[226:227]
	v_pk_fma_f32 v[210:211], v[90:91], v[252:253], v[228:229]
	v_fmac_f32_dpp v208, v88, v242 row_shr:1 row_mask:0xf bank_mask:0xf
	v_fmac_f32_dpp v209, v89, v243 row_shr:1 row_mask:0xf bank_mask:0xf
	v_fmac_f32_dpp v210, v90, v244 row_shr:1 row_mask:0xf bank_mask:0xf
	v_fmac_f32_dpp v211, v91, v245 row_shr:1 row_mask:0xf bank_mask:0xf
	v_fmac_f32_dpp v208, v88, v234 row_shr:2 row_mask:0xf bank_mask:0xf
	v_fmac_f32_dpp v209, v89, v235 row_shr:2 row_mask:0xf bank_mask:0xf
	v_fmac_f32_dpp v210, v90, v236 row_shr:2 row_mask:0xf bank_mask:0xf
	v_fmac_f32_dpp v211, v91, v237 row_shr:2 row_mask:0xf bank_mask:0xf
	v_fmac_f32_dpp v208, v112, v200 row_shl:2 row_mask:0xf bank_mask:0xf
	v_fmac_f32_dpp v209, v113, v200 row_shl:2 row_mask:0xf bank_mask:0xf
	v_fmac_f32_dpp v210, v114, v200 row_shl:2 row_mask:0xf bank_mask:0xf
	v_fmac_f32_dpp v211, v115, v200 row_shl:2 row_mask:0xf bank_mask:0xf
	v_pk_mul_f32 v[86:87], v[208:209], v[208:209]
	v_pk_mul_f32 v[92:93], v[210:211], v[210:211]
	v_pk_fma_f32 v[86:87], v[86:87], s[74:75], v[154:155] op_sel_hi:[1,0,1]
	v_pk_fma_f32 v[92:93], v[92:93], s[74:75], v[154:155] op_sel_hi:[1,0,1]
	v_pk_mul_f32 v[86:87], v[208:209], v[86:87]
	v_pk_mul_f32 v[92:93], v[210:211], v[92:93]
	v_exp_f32_e32 v86, v86
	v_exp_f32_e32 v87, v87
	v_exp_f32_e32 v92, v92
	v_exp_f32_e32 v93, v93
	v_pk_mul_f32 v[208:209], v[208:209], v[82:83]
	v_pk_mul_f32 v[210:211], v[210:211], v[84:85]
	v_pk_add_f32 v[86:87], v[86:87], v[152:153]
	v_pk_add_f32 v[92:93], v[92:93], v[152:153]
	v_rcp_f32_e32 v86, v86
	v_rcp_f32_e32 v87, v87
	v_rcp_f32_e32 v92, v92
	v_rcp_f32_e32 v93, v93
	s_nop 0
	v_pk_mul_f32 v[208:209], v[208:209], v[86:87]
	v_pk_mul_f32 v[210:211], v[210:211], v[92:93]
	v_cvt_pk_bf16_f32 v82, v208, v209
	v_cvt_pk_bf16_f32 v83, v210, v211
	v_pk_fma_f32 v[208:209], v[22:23], v[204:205], v[230:231]
	v_pk_fma_f32 v[210:211], v[24:25], v[206:207], v[232:233]
	v_fmac_f32_dpp v208, v22, v246 row_shr:1 row_mask:0xf bank_mask:0xf
	v_fmac_f32_dpp v209, v23, v247 row_shr:1 row_mask:0xf bank_mask:0xf
	v_fmac_f32_dpp v210, v24, v248 row_shr:1 row_mask:0xf bank_mask:0xf
	v_fmac_f32_dpp v211, v25, v249 row_shr:1 row_mask:0xf bank_mask:0xf
	v_fmac_f32_dpp v208, v22, v238 row_shr:2 row_mask:0xf bank_mask:0xf
	v_fmac_f32_dpp v209, v23, v239 row_shr:2 row_mask:0xf bank_mask:0xf
	v_fmac_f32_dpp v210, v24, v240 row_shr:2 row_mask:0xf bank_mask:0xf
	v_fmac_f32_dpp v211, v25, v241 row_shr:2 row_mask:0xf bank_mask:0xf
	v_fmac_f32_dpp v208, v116, v200 row_shl:2 row_mask:0xf bank_mask:0xf
	v_fmac_f32_dpp v209, v117, v200 row_shl:2 row_mask:0xf bank_mask:0xf
;     __device__ __forceinline__ void operator()(const f32x4 (&acc)[2][2][4][2], const Unit& u, int wr, int wc, int fr, int fq) const {
;     ...
;                     const int r = row0 + ai * HALF + m * 16; const float rs = rstd[ai][m];
;                     const f32x4 a = acc[ai][0][m][n] * rs, b = acc[ai][1][m][n] * rs; f32x4 p1, p2;
;                     if (!smp) {
; #pragma unroll
;                         for (int e2 = 0; e2 < 4; ++e2) { const float s1 = fr == 15 ? pa[e2] : a[e2], s2 = fr >= 14 ? pa[e2] : a[e2]; p1[e2] = ror1(s1); p2[e2] = ror2(s2); }
;                         if (ai == 0 && wr == 0 && m == 0 && fr < 2) { *(f32x4*)(EA + ((size_t)u.pm * 4 + fr) * FF + j0 + 4 * n) = a; *(f32x4*)(EB + ((size_t)u.pm * 2 + fr) * FF + j0 + 4 * n) = b; }
;                         if (ai == 1 && wr == 1 && m == 3 && fr >= 14) { *(f32x4*)(EA + ((size_t)u.pm * 4 + 2 + (fr - 14)) * FF + j0 + 4 * n) = a;
;                             if ((u.pm & 7) == 7) *(f32x4*)(o_conv_p + ((size_t)(u.pm >> 3) * 2 + (fr - 14)) * FF + j0 + 4 * n) = a; }
;                     } else {
;                         const int t = fr & 7, bb = (r - 16384) >> 3;
; #pragma unroll
;                         for (int e2 = 0; e2 < 4; ++e2) { p1[e2] = ror1(a[e2]); p2[e2] = ror2(a[e2]); }
;                         if (t < 2) { const f32x4 h1 = *(const f32x4*)(state_conv + ((size_t)bb * 2 + 1) * FF + j0 + 4 * n);
;                             if (t == 0) { p1 = h1; p2 = *(const f32x4*)(state_conv + ((size_t)bb * 2) * FF + j0 + 4 * n); } else p2 = h1; }
;                         if (t >= 6) *(f32x4*)(o_conv_s + ((size_t)bb * 2 + (t - 6)) * FF + j0 + 4 * n) = a;
;                     }
;                     f32x4 hv;
; #pragma unroll
;                     for (int e2 = 0; e2 < 1; ++e2) {
;                         const f32x4 c4 = cb + w0 * p2 + w1 * p1 + w2 * a;
;                         const f32x4 z = c4 * ((c4 * c4) * (-0.10294324f) + (-2.3022082f));
;                         f32x4 den; den[0] = 1.f + __builtin_amdgcn_exp2f(z[0]); den[1] = 1.f + __builtin_amdgcn_exp2f(z[1]); den[2] = 1.f + __builtin_amdgcn_exp2f(z[2]); den[3] = 1.f + __builtin_amdgcn_exp2f(z[3]);
;                         f32x4 rc; rc[0] = frcp(den[0]); rc[1] = frcp(den[1]); rc[2] = frcp(den[2]); rc[3] = frcp(den[3]);
;                         hv = (c4 * rc) * b; }
	v_fmac_f32_dpp v210, v118, v200 row_shl:2 row_mask:0xf bank_mask:0xf
	v_fmac_f32_dpp v211, v119, v200 row_shl:2 row_mask:0xf bank_mask:0xf
	v_pk_mul_f32 v[86:87], v[208:209], v[208:209]
	v_pk_mul_f32 v[92:93], v[210:211], v[210:211]
	v_pk_fma_f32 v[86:87], v[86:87], s[74:75], v[154:155] op_sel_hi:[1,0,1]
	v_pk_fma_f32 v[92:93], v[92:93], s[74:75], v[154:155] op_sel_hi:[1,0,1]
	v_pk_mul_f32 v[86:87], v[208:209], v[86:87]
	v_pk_mul_f32 v[92:93], v[210:211], v[92:93]
	v_exp_f32_e32 v86, v86
	v_exp_f32_e32 v87, v87
	v_exp_f32_e32 v92, v92
	v_exp_f32_e32 v93, v93
	v_pk_mul_f32 v[208:209], v[208:209], v[18:19]
	v_pk_mul_f32 v[210:211], v[210:211], v[20:21]
	v_pk_add_f32 v[86:87], v[86:87], v[152:153]
	v_pk_add_f32 v[92:93], v[92:93], v[152:153]
	v_rcp_f32_e32 v86, v86
	v_rcp_f32_e32 v87, v87
	v_rcp_f32_e32 v92, v92
	v_rcp_f32_e32 v93, v93
	s_nop 0
	v_pk_mul_f32 v[208:209], v[208:209], v[86:87]
	v_pk_mul_f32 v[210:211], v[210:211], v[92:93]
	v_cvt_pk_bf16_f32 v84, v208, v209
	v_cvt_pk_bf16_f32 v85, v210, v211
	s_mov_b64 exec, s[84:85]
	global_store_dwordx4 v98, v[88:91], s[42:43]
	global_store_dwordx4 v98, v[22:25], s[42:43] offset:16
	s_mov_b64 exec, -1
	global_store_dwordx4 v212, v[82:85], s[80:81]
	s_add_u32 s42, s42, 0xb000
	s_addc_u32 s43, s43, 0
	s_add_u32 s80, s80, 0x16000
	s_addc_u32 s81, s81, 0
	v_pk_fma_f32 v[208:209], v[78:79], v[250:251], v[226:227]
	v_pk_fma_f32 v[210:211], v[80:81], v[252:253], v[228:229]
	v_fmac_f32_dpp v208, v78, v242 row_shr:1 row_mask:0xf bank_mask:0xf
	v_fmac_f32_dpp v209, v79, v243 row_shr:1 row_mask:0xf bank_mask:0xf
	v_fmac_f32_dpp v210, v80, v244 row_shr:1 row_mask:0xf bank_mask:0xf
	v_fmac_f32_dpp v211, v81, v245 row_shr:1 row_mask:0xf bank_mask:0xf
	v_fmac_f32_dpp v208, v78, v234 row_shr:2 row_mask:0xf bank_mask:0xf
	v_fmac_f32_dpp v209, v79, v235 row_shr:2 row_mask:0xf bank_mask:0xf
	v_fmac_f32_dpp v210, v80, v236 row_shr:2 row_mask:0xf bank_mask:0xf
	v_fmac_f32_dpp v211, v81, v237 row_shr:2 row_mask:0xf bank_mask:0xf
	v_fmac_f32_dpp v208, v112, v200 row_shl:4 row_mask:0xf bank_mask:0xf
	v_fmac_f32_dpp v209, v113, v200 row_shl:4 row_mask:0xf bank_mask:0xf
	v_fmac_f32_dpp v210, v114, v200 row_shl:4 row_mask:0xf bank_mask:0xf
	v_fmac_f32_dpp v211, v115, v200 row_shl:4 row_mask:0xf bank_mask:0xf
	v_pk_mul_f32 v[86:87], v[208:209], v[208:209]
	v_pk_mul_f32 v[92:93], v[210:211], v[210:211]
	v_pk_fma_f32 v[86:87], v[86:87], s[74:75], v[154:155] op_sel_hi:[1,0,1]
	v_pk_fma_f32 v[92:93], v[92:93], s[74:75], v[154:155] op_sel_hi:[1,0,1]
	v_pk_mul_f32 v[86:87], v[208:209], v[86:87]
	v_pk_mul_f32 v[92:93], v[210:211], v[92:93]
	v_exp_f32_e32 v86, v86
	v_exp_f32_e32 v87, v87
	v_exp_f32_e32 v92, v92
	v_exp_f32_e32 v93, v93
	v_pk_mul_f32 v[208:209], v[208:209], v[70:71]
	v_pk_mul_f32 v[210:211], v[210:211], v[72:73]
	v_pk_add_f32 v[86:87], v[86:87], v[152:153]
	v_pk_add_f32 v[92:93], v[92:93], v[152:153]
	v_rcp_f32_e32 v86, v86
	v_rcp_f32_e32 v87, v87
	v_rcp_f32_e32 v92, v92
	v_rcp_f32_e32 v93, v93
	s_nop 0
	v_pk_mul_f32 v[208:209], v[208:209], v[86:87]
	v_pk_mul_f32 v[210:211], v[210:211], v[92:93]
	v_cvt_pk_bf16_f32 v70, v208, v209
	v_cvt_pk_bf16_f32 v71, v210, v211
	v_pk_fma_f32 v[208:209], v[14:15], v[204:205], v[230:231]
	v_pk_fma_f32 v[210:211], v[16:17], v[206:207], v[232:233]
	v_fmac_f32_dpp v208, v14, v246 row_shr:1 row_mask:0xf bank_mask:0xf
	v_fmac_f32_dpp v209, v15, v247 row_shr:1 row_mask:0xf bank_mask:0xf
	v_fmac_f32_dpp v210, v16, v248 row_shr:1 row_mask:0xf bank_mask:0xf
	v_fmac_f32_dpp v211, v17, v249 row_shr:1 row_mask:0xf bank_mask:0xf
	v_fmac_f32_dpp v208, v14, v238 row_shr:2 row_mask:0xf bank_mask:0xf
	v_fmac_f32_dpp v209, v15, v239 row_shr:2 row_mask:0xf bank_mask:0xf
	v_fmac_f32_dpp v210, v16, v240 row_shr:2 row_mask:0xf bank_mask:0xf
	v_fmac_f32_dpp v211, v17, v241 row_shr:2 row_mask:0xf bank_mask:0xf
	v_fmac_f32_dpp v208, v116, v200 row_shl:4 row_mask:0xf bank_mask:0xf
	v_fmac_f32_dpp v209, v117, v200 row_shl:4 row_mask:0xf bank_mask:0xf
	v_fmac_f32_dpp v210, v118, v200 row_shl:4 row_mask:0xf bank_mask:0xf
	v_fmac_f32_dpp v211, v119, v200 row_shl:4 row_mask:0xf bank_mask:0xf
	v_pk_mul_f32 v[86:87], v[208:209], v[208:209]
	v_pk_mul_f32 v[92:93], v[210:211], v[210:211]
	v_pk_fma_f32 v[86:87], v[86:87], s[74:75], v[154:155] op_sel_hi:[1,0,1]
	v_pk_fma_f32 v[92:93], v[92:93], s[74:75], v[154:155] op_sel_hi:[1,0,1]
	v_pk_mul_f32 v[86:87], v[208:209], v[86:87]
	v_pk_mul_f32 v[92:93], v[210:211], v[92:93]
	v_exp_f32_e32 v86, v86
	v_exp_f32_e32 v87, v87
	v_exp_f32_e32 v92, v92
	v_exp_f32_e32 v93, v93
	v_pk_mul_f32 v[208:209], v[208:209], v[10:11]
;     __device__ __forceinline__ void operator()(const f32x4 (&acc)[2][2][4][2], const Unit& u, int wr, int wc, int fr, int fq) const {
;     ...
;                     const int r = row0 + ai * HALF + m * 16; const float rs = rstd[ai][m];
;                     const f32x4 a = acc[ai][0][m][n] * rs, b = acc[ai][1][m][n] * rs; f32x4 p1, p2;
;                     if (!smp) {
; #pragma unroll
;                         for (int e2 = 0; e2 < 4; ++e2) { const float s1 = fr == 15 ? pa[e2] : a[e2], s2 = fr >= 14 ? pa[e2] : a[e2]; p1[e2] = ror1(s1); p2[e2] = ror2(s2); }
;                         if (ai == 0 && wr == 0 && m == 0 && fr < 2) { *(f32x4*)(EA + ((size_t)u.pm * 4 + fr) * FF + j0 + 4 * n) = a; *(f32x4*)(EB + ((size_t)u.pm * 2 + fr) * FF + j0 + 4 * n) = b; }
;                         if (ai == 1 && wr == 1 && m == 3 && fr >= 14) { *(f32x4*)(EA + ((size_t)u.pm * 4 + 2 + (fr - 14)) * FF + j0 + 4 * n) = a;
;                             if ((u.pm & 7) == 7) *(f32x4*)(o_conv_p + ((size_t)(u.pm >> 3) * 2 + (fr - 14)) * FF + j0 + 4 * n) = a; }
;                     } else {
;                         const int t = fr & 7, bb = (r - 16384) >> 3;
; #pragma unroll
;                         for (int e2 = 0; e2 < 4; ++e2) { p1[e2] = ror1(a[e2]); p2[e2] = ror2(a[e2]); }
;                         if (t < 2) { const f32x4 h1 = *(const f32x4*)(state_conv + ((size_t)bb * 2 + 1) * FF + j0 + 4 * n);
;                             if (t == 0) { p1 = h1; p2 = *(const f32x4*)(state_conv + ((size_t)bb * 2) * FF + j0 + 4 * n); } else p2 = h1; }
;                         if (t >= 6) *(f32x4*)(o_conv_s + ((size_t)bb * 2 + (t - 6)) * FF + j0 + 4 * n) = a;
;                     }
;                     f32x4 hv;
; #pragma unroll
;                     for (int e2 = 0; e2 < 1; ++e2) {
;                         const f32x4 c4 = cb + w0 * p2 + w1 * p1 + w2 * a;
;                         const f32x4 z = c4 * ((c4 * c4) * (-0.10294324f) + (-2.3022082f));
;                         f32x4 den; den[0] = 1.f + __builtin_amdgcn_exp2f(z[0]); den[1] = 1.f + __builtin_amdgcn_exp2f(z[1]); den[2] = 1.f + __builtin_amdgcn_exp2f(z[2]); den[3] = 1.f + __builtin_amdgcn_exp2f(z[3]);
;                         f32x4 rc; rc[0] = frcp(den[0]); rc[1] = frcp(den[1]); rc[2] = frcp(den[2]); rc[3] = frcp(den[3]);
;                         hv = (c4 * rc) * b; }
	v_pk_mul_f32 v[210:211], v[210:211], v[12:13]
	v_pk_add_f32 v[86:87], v[86:87], v[152:153]
	v_pk_add_f32 v[92:93], v[92:93], v[152:153]
	v_rcp_f32_e32 v86, v86
	v_rcp_f32_e32 v87, v87
	v_rcp_f32_e32 v92, v92
	v_rcp_f32_e32 v93, v93
	s_nop 0
	v_pk_mul_f32 v[208:209], v[208:209], v[86:87]
	v_pk_mul_f32 v[210:211], v[210:211], v[92:93]
	v_cvt_pk_bf16_f32 v72, v208, v209
	v_cvt_pk_bf16_f32 v73, v210, v211
	s_mov_b64 exec, s[84:85]
	global_store_dwordx4 v98, v[78:81], s[42:43]
	global_store_dwordx4 v98, v[14:17], s[42:43] offset:16
	s_mov_b64 exec, -1
	global_store_dwordx4 v212, v[70:73], s[80:81]
	s_add_u32 s42, s42, 0xb000
	s_addc_u32 s43, s43, 0
	s_add_u32 s80, s80, 0x16000
	s_addc_u32 s81, s81, 0
	v_pk_fma_f32 v[208:209], v[74:75], v[250:251], v[226:227]
	v_pk_fma_f32 v[210:211], v[76:77], v[252:253], v[228:229]
	v_fmac_f32_dpp v208, v74, v242 row_shr:1 row_mask:0xf bank_mask:0xf
	v_fmac_f32_dpp v209, v75, v243 row_shr:1 row_mask:0xf bank_mask:0xf
	v_fmac_f32_dpp v210, v76, v244 row_shr:1 row_mask:0xf bank_mask:0xf
	v_fmac_f32_dpp v211, v77, v245 row_shr:1 row_mask:0xf bank_mask:0xf
	v_fmac_f32_dpp v208, v74, v234 row_shr:2 row_mask:0xf bank_mask:0xf
	v_fmac_f32_dpp v209, v75, v235 row_shr:2 row_mask:0xf bank_mask:0xf
	v_fmac_f32_dpp v210, v76, v236 row_shr:2 row_mask:0xf bank_mask:0xf
	v_fmac_f32_dpp v211, v77, v237 row_shr:2 row_mask:0xf bank_mask:0xf
	v_fmac_f32_dpp v208, v112, v200 row_shl:6 row_mask:0xf bank_mask:0xf
	v_fmac_f32_dpp v209, v113, v200 row_shl:6 row_mask:0xf bank_mask:0xf
	v_fmac_f32_dpp v210, v114, v200 row_shl:6 row_mask:0xf bank_mask:0xf
	v_fmac_f32_dpp v211, v115, v200 row_shl:6 row_mask:0xf bank_mask:0xf
	v_pk_mul_f32 v[86:87], v[208:209], v[208:209]
	v_pk_mul_f32 v[92:93], v[210:211], v[210:211]
	v_pk_fma_f32 v[86:87], v[86:87], s[74:75], v[154:155] op_sel_hi:[1,0,1]
	v_pk_fma_f32 v[92:93], v[92:93], s[74:75], v[154:155] op_sel_hi:[1,0,1]
	v_pk_mul_f32 v[86:87], v[208:209], v[86:87]
	v_pk_mul_f32 v[92:93], v[210:211], v[92:93]
	v_exp_f32_e32 v86, v86
	v_exp_f32_e32 v87, v87
	v_exp_f32_e32 v92, v92
	v_exp_f32_e32 v93, v93
	v_pk_mul_f32 v[208:209], v[208:209], v[66:67]
	v_pk_mul_f32 v[210:211], v[210:211], v[68:69]
	v_pk_add_f32 v[86:87], v[86:87], v[152:153]
	v_pk_add_f32 v[92:93], v[92:93], v[152:153]
	v_rcp_f32_e32 v86, v86
	v_rcp_f32_e32 v87, v87
	v_rcp_f32_e32 v92, v92
	v_rcp_f32_e32 v93, v93
	s_nop 0
	v_pk_mul_f32 v[208:209], v[208:209], v[86:87]
	v_pk_mul_f32 v[210:211], v[210:211], v[92:93]
	v_cvt_pk_bf16_f32 v66, v208, v209
	v_cvt_pk_bf16_f32 v67, v210, v211
	v_pk_fma_f32 v[208:209], v[6:7], v[204:205], v[230:231]
	v_pk_fma_f32 v[210:211], v[8:9], v[206:207], v[232:233]
	v_fmac_f32_dpp v208, v6, v246 row_shr:1 row_mask:0xf bank_mask:0xf
	v_fmac_f32_dpp v209, v7, v247 row_shr:1 row_mask:0xf bank_mask:0xf
	v_fmac_f32_dpp v210, v8, v248 row_shr:1 row_mask:0xf bank_mask:0xf
	v_fmac_f32_dpp v211, v9, v249 row_shr:1 row_mask:0xf bank_mask:0xf
	v_fmac_f32_dpp v208, v6, v238 row_shr:2 row_mask:0xf bank_mask:0xf
	v_fmac_f32_dpp v209, v7, v239 row_shr:2 row_mask:0xf bank_mask:0xf
	v_fmac_f32_dpp v210, v8, v240 row_shr:2 row_mask:0xf bank_mask:0xf
	v_fmac_f32_dpp v211, v9, v241 row_shr:2 row_mask:0xf bank_mask:0xf
	v_fmac_f32_dpp v208, v116, v200 row_shl:6 row_mask:0xf bank_mask:0xf
	v_fmac_f32_dpp v209, v117, v200 row_shl:6 row_mask:0xf bank_mask:0xf
	v_fmac_f32_dpp v210, v118, v200 row_shl:6 row_mask:0xf bank_mask:0xf
	v_fmac_f32_dpp v211, v119, v200 row_shl:6 row_mask:0xf bank_mask:0xf
	v_pk_mul_f32 v[86:87], v[208:209], v[208:209]
	v_pk_mul_f32 v[92:93], v[210:211], v[210:211]
	v_pk_fma_f32 v[86:87], v[86:87], s[74:75], v[154:155] op_sel_hi:[1,0,1]
	v_pk_fma_f32 v[92:93], v[92:93], s[74:75], v[154:155] op_sel_hi:[1,0,1]
	v_pk_mul_f32 v[86:87], v[208:209], v[86:87]
	v_pk_mul_f32 v[92:93], v[210:211], v[92:93]
	v_exp_f32_e32 v86, v86
	v_exp_f32_e32 v87, v87
	v_exp_f32_e32 v92, v92
	v_exp_f32_e32 v93, v93
	v_pk_mul_f32 v[208:209], v[208:209], v[2:3]
	v_pk_mul_f32 v[210:211], v[210:211], v[4:5]
	v_pk_add_f32 v[86:87], v[86:87], v[152:153]
	v_pk_add_f32 v[92:93], v[92:93], v[152:153]
	v_rcp_f32_e32 v86, v86
	v_rcp_f32_e32 v87, v87
	v_rcp_f32_e32 v92, v92
	v_rcp_f32_e32 v93, v93
	s_nop 0
	v_pk_mul_f32 v[208:209], v[208:209], v[86:87]
	v_pk_mul_f32 v[210:211], v[210:211], v[92:93]
	v_cvt_pk_bf16_f32 v68, v208, v209
	v_cvt_pk_bf16_f32 v69, v210, v211
	s_mov_b64 exec, s[84:85]
	global_store_dwordx4 v98, v[74:77], s[42:43]
	global_store_dwordx4 v98, v[6:9], s[42:43] offset:16
	s_mov_b64 exec, -1
	global_store_dwordx4 v212, v[66:69], s[80:81]
	s_branch .Lepi5_done
